# LN loops: contiguous row block per wave, mods loaded once per cond; first grid sync through the XCD barrier
# speedup vs baseline: 1.0325x; 1.0032x over previous
.LBB0_30:
	v_readlane_b32 s16, v252, 24
	v_readlane_b32 s20, v252, 28
	v_readlane_b32 s34, v255, 5
	v_readlane_b32 s17, v252, 25
	v_readlane_b32 s21, v252, 29
	v_readlane_b32 s35, v255, 6
	s_add_u32 s16, s20, s34
	s_addc_u32 s17, s21, s35
	v_readlane_b32 s22, v252, 30
	v_writelane_b32 v255, s16, 9
	v_readlane_b32 s23, v252, 31
	v_readlane_b32 s18, v252, 26
	v_writelane_b32 v255, s17, 10
	s_add_u32 s16, s22, s34
	s_addc_u32 s17, s23, s35
	v_readlane_b32 s19, v252, 27
	v_readlane_b32 s24, v252, 32
	v_readlane_b32 s25, v252, 33
	v_readlane_b32 s26, v252, 34
	v_readlane_b32 s27, v252, 35
	v_readlane_b32 s28, v252, 36
	v_readlane_b32 s29, v252, 37
	v_readlane_b32 s30, v252, 38
	v_readlane_b32 s31, v252, 39
	v_writelane_b32 v255, s16, 11
	s_mov_b64 s[42:43], -1
	s_nop 0
	v_writelane_b32 v255, s17, 12
	v_readlane_b32 s16, v252, 40
	v_readlane_b32 s17, v252, 41
	s_add_u32 s16, s16, s34
	s_addc_u32 s17, s17, s35
	v_readlane_b32 s18, v252, 42
	v_writelane_b32 v255, s16, 13
	v_readlane_b32 s19, v252, 43
	v_readlane_b32 s20, v252, 44
	v_writelane_b32 v255, s17, 14
	s_add_u32 s16, s18, s34
	s_addc_u32 s17, s19, s35
	v_readlane_b32 s21, v252, 45
	s_add_u32 s66, s20, s34
	s_addc_u32 s67, s21, s35
	s_add_i32 s2, s0, s2
	s_and_b32 s0, s1, 1
	v_writelane_b32 v255, s16, 15
	s_bitcmp1_b32 s1, 0
	v_readlane_b32 s22, v252, 46
	v_writelane_b32 v255, s17, 16
	s_cselect_b64 s[16:17], -1, 0
	s_cmp_eq_u32 s0, 0
	s_cselect_b64 s[44:45], -1, 0
	v_writelane_b32 v255, s1, 17
	s_and_b64 s[0:1], s[44:45], exec
	v_writelane_b32 v255, s16, 18
	s_cselect_b32 s0, -3, -6
	s_add_i32 s0, s0, s2
	v_writelane_b32 v255, s17, 19
	v_writelane_b32 v255, s2, 20
	s_cmp_gt_i32 s0, -1
	v_readlane_b32 s23, v252, 47
	v_readlane_b32 s24, v252, 48
	v_readlane_b32 s25, v252, 49
	v_readlane_b32 s26, v252, 50
	v_readlane_b32 s27, v252, 51
	v_readlane_b32 s28, v252, 52
	v_readlane_b32 s29, v252, 53
	v_readlane_b32 s30, v252, 54
	v_readlane_b32 s31, v252, 55
	s_cbranch_scc0 .LBB0_281
	s_cmp_lt_i32 s0, 1
	s_cbranch_scc1 .LBB0_271
	s_cmp_lt_i32 s0, 2
	s_cbranch_scc1 .LBB0_211
	s_cmp_lg_u32 s0, 2
	s_cbranch_scc0 .LBB0_190
	s_xor_b64 s[0:1], s[40:41], -1
	s_mov_b64 s[40:41], -1
	s_and_b64 vcc, exec, s[0:1]
	s_cbranch_vccz .LBB0_185
	v_readlane_b32 s0, v255, 17
	s_add_i32 s7, s0, 1
	v_readfirstlane_b32 s0, v155
	v_mbcnt_lo_u32_b32 v0, -1, 0
	v_mbcnt_hi_u32_b32 v0, -1, v0
	s_waitcnt vmcnt(0) lgkmcnt(0)
	s_nop 0
	v_or_b32_e32 v1, s0, v0
	v_readlane_b32 s0, v252, 59
	v_readlane_b32 s1, v252, 60
	s_load_dword s2, s[0:1], 0x0
	v_ashrrev_i32_e32 v1, 5, v1
	v_and_b32_e32 v1, -2, v1
	v_readlane_b32 s0, v252, 58
	s_nop 1
	v_add_u32_e32 v32, s0, v1
	s_mov_b32 s0, 0x9000
	v_cmp_gt_i32_e32 vcc, s0, v32
	s_and_saveexec_b64 s[42:43], vcc
	s_cbranch_execz .LBB0_42
	v_readlane_b32 s0, v255, 17
	s_lshl_b32 s0, s0, 13
	s_or_b32 s28, s0, 0x1000
	v_readlane_b32 s0, v255, 9
	v_readlane_b32 s1, v255, 10
	s_add_u32 s0, s0, s28
	v_and_b32_e32 v40, 63, v0
	s_addc_u32 s1, s1, 0
	v_readlane_b32 s16, v255, 11
	v_readlane_b32 s17, v255, 12
	s_add_u32 s28, s16, s28
	v_lshlrev_b32_e32 v34, 4, v40
	s_addc_u32 s29, s17, 0
	global_load_dwordx4 v[0:3], v34, s[0:1]
	global_load_dwordx4 v[4:7], v34, s[0:1] offset:1024
	global_load_dwordx4 v[8:11], v34, s[28:29]
	global_load_dwordx4 v[12:15], v34, s[28:29] offset:1024
	global_load_dwordx4 v[16:19], v34, s[0:1] offset:2048
	global_load_dwordx4 v[20:23], v34, s[0:1] offset:3072
	global_load_dwordx4 v[24:27], v34, s[28:29] offset:2048
	global_load_dwordx4 v[28:31], v34, s[28:29] offset:3072
	v_lshlrev_b32_e32 v33, 2, v40
	v_xor_b32_e32 v77, 0x80, v33
	v_xor_b32_e32 v78, 64, v33
	v_xor_b32_e32 v79, 32, v33
	v_xor_b32_e32 v80, 16, v33
	v_xor_b32_e32 v81, 8, v33
	v_xor_b32_e32 v82, 4, v33
	v_ashrrev_i32_e32 v33, 31, v32
	s_waitcnt lgkmcnt(0)
	s_lshl_b32 s50, s2, 4
	v_readlane_b32 s68, v254, 44
	v_lshlrev_b64 v[38:39], 11, v[32:33]
	v_mov_b32_e32 v35, v153
	v_readlane_b32 s72, v254, 48
	v_readlane_b32 s73, v254, 49
	s_ashr_i32 s51, s50, 31
	v_lshl_or_b32 v38, v40, 3, v38
	v_cmp_eq_u32_e64 s[40:41], 0, v40
	s_mul_i32 s0, s7, 9
	v_lshl_add_u64 v[34:35], s[58:59], 0, v[34:35]
	v_lshl_add_u64 v[36:37], v[32:33], 3, s[72:73]
	s_lshl_b64 s[52:53], s[50:51], 3
	v_lshl_add_u64 v[38:39], s[72:73], 0, v[38:39]
	s_lshl_b64 s[54:55], s[50:51], 11
	s_mov_b64 s[88:89], 0
	v_readlane_b32 s69, v254, 45
	v_readlane_b32 s70, v254, 46
	v_readlane_b32 s71, v254, 47
	v_readlane_b32 s74, v254, 50
	v_readlane_b32 s75, v254, 51
	s_mov_b64 s[40:41], exec
	v_readfirstlane_b32 s72, v32
	v_lshlrev_b32_e32 v41, 3, v40
	v_lshlrev_b32_e32 v42, 4, v40
	v_add_u32_e32 v43, 0x1000, v42
	s_nop 3
	s_lshr_b32 s16, s50, 1
	s_mov_b32 s17, 0
	s_mov_b32 s1, 0
.Llna_div:
	s_add_i32 s17, s17, s16
	s_add_i32 s1, s1, 1
	s_cmpk_lt_u32 s17, 0x4800
	s_cbranch_scc1 .Llna_div
	s_lshl_b32 s1, s1, 1
	s_lshr_b32 s72, s72, 1
	s_mul_i32 s72, s72, s1
	s_add_i32 s74, s72, s1
	s_min_i32 s74, s74, 0x9000
	s_mov_b32 s75, -1
	s_cmp_ge_i32 s72, s74
	s_cbranch_scc1 .Llna_exit
	s_lshl_b32 s1, s72, 11
	s_add_u32 s28, s58, s1
	s_addc_u32 s29, s59, 0
	s_add_u32 s28, s28, 0xa10000
	s_addc_u32 s29, s29, 0
	global_load_dwordx2 v[44:45], v41, s[28:29] nt
	global_load_dwordx2 v[46:47], v41, s[28:29] offset:512 nt
	global_load_dwordx2 v[48:49], v41, s[28:29] offset:1024 nt
	global_load_dwordx2 v[50:51], v41, s[28:29] offset:1536 nt
	global_load_dwordx2 v[52:53], v41, s[28:29] offset:2048 nt
	global_load_dwordx2 v[54:55], v41, s[28:29] offset:2560 nt
	global_load_dwordx2 v[56:57], v41, s[28:29] offset:3072 nt
	global_load_dwordx2 v[58:59], v41, s[28:29] offset:3584 nt
	s_lshl_b32 s1, s72, 11
	s_add_u32 s54, s58, s1
	s_addc_u32 s55, s59, 0
	s_add_u32 s54, s54, 0x9a10000
	s_addc_u32 s55, s55, 0
	s_lshl_b32 s1, s72, 3
	s_add_u32 s68, s58, s1
	s_addc_u32 s69, s59, 0
	s_add_u32 s68, s68, 0x910000
	s_addc_u32 s69, s69, 0
	s_lshr_b32 s1, s72, 12
	s_cmp_eq_u32 s1, s75
	s_cbranch_scc1 .Llna_mk0
	s_mov_b32 s75, s1
	s_add_i32 s1, s1, s0
	s_mul_i32 s1, s1, 0x6000
	s_add_u32 s70, s58, s1
	s_addc_u32 s71, s59, 0
	global_load_dwordx4 v[116:119], v42, s[70:71]
	global_load_dwordx4 v[120:123], v42, s[70:71] offset:1024
	global_load_dwordx4 v[124:127], v42, s[70:71] offset:2048
	global_load_dwordx4 v[128:131], v42, s[70:71] offset:3072
	global_load_dwordx4 v[132:135], v43, s[70:71]
	global_load_dwordx4 v[136:139], v43, s[70:71] offset:1024
	global_load_dwordx4 v[140:143], v43, s[70:71] offset:2048
	global_load_dwordx4 v[144:147], v43, s[70:71] offset:3072
	s_waitcnt vmcnt(0)
	v_pk_add_f32 v[132:133], v[132:133], 1.0 op_sel_hi:[1,0]
	v_pk_add_f32 v[134:135], v[134:135], 1.0 op_sel_hi:[1,0]
	v_pk_add_f32 v[136:137], v[136:137], 1.0 op_sel_hi:[1,0]
	v_pk_add_f32 v[138:139], v[138:139], 1.0 op_sel_hi:[1,0]
	v_pk_add_f32 v[140:141], v[140:141], 1.0 op_sel_hi:[1,0]
	v_pk_add_f32 v[142:143], v[142:143], 1.0 op_sel_hi:[1,0]
	v_pk_add_f32 v[144:145], v[144:145], 1.0 op_sel_hi:[1,0]
	v_pk_add_f32 v[146:147], v[146:147], 1.0 op_sel_hi:[1,0]
.Llna_mk0:
	s_add_i32 s73, s72, 2
	s_cmp_ge_i32 s73, s74
	s_cbranch_scc1 .Llna_np0
	s_lshl_b32 s1, s73, 11
	s_add_u32 s28, s58, s1
	s_addc_u32 s29, s59, 0
	s_add_u32 s28, s28, 0xa10000
	s_addc_u32 s29, s29, 0
	global_load_dwordx2 v[60:61], v41, s[28:29] nt
	global_load_dwordx2 v[62:63], v41, s[28:29] offset:512 nt
	global_load_dwordx2 v[64:65], v41, s[28:29] offset:1024 nt
	global_load_dwordx2 v[66:67], v41, s[28:29] offset:1536 nt
	global_load_dwordx2 v[68:69], v41, s[28:29] offset:2048 nt
	global_load_dwordx2 v[70:71], v41, s[28:29] offset:2560 nt
	global_load_dwordx2 v[72:73], v41, s[28:29] offset:3072 nt
	global_load_dwordx2 v[74:75], v41, s[28:29] offset:3584 nt
	s_waitcnt vmcnt(8)
	s_branch .Llna_go0

.Llna_go0:
	v_lshlrev_b32_e32 v84, 16, v44
	v_and_b32_e32 v86, 0xffff0000, v44
	v_lshlrev_b32_e32 v88, 16, v45
	v_and_b32_e32 v90, 0xffff0000, v45
	v_lshlrev_b32_e32 v92, 16, v46
	v_and_b32_e32 v94, 0xffff0000, v46
	v_lshlrev_b32_e32 v96, 16, v47
	v_and_b32_e32 v98, 0xffff0000, v47
	v_lshlrev_b32_e32 v100, 16, v48
	v_and_b32_e32 v102, 0xffff0000, v48
	v_lshlrev_b32_e32 v104, 16, v49
	v_and_b32_e32 v106, 0xffff0000, v49
	v_lshlrev_b32_e32 v108, 16, v50
	v_and_b32_e32 v110, 0xffff0000, v50
	v_lshlrev_b32_e32 v112, 16, v51
	v_and_b32_e32 v114, 0xffff0000, v51
	v_lshlrev_b32_e32 v85, 16, v52
	v_and_b32_e32 v87, 0xffff0000, v52
	v_lshlrev_b32_e32 v89, 16, v53
	v_and_b32_e32 v91, 0xffff0000, v53
	v_lshlrev_b32_e32 v93, 16, v54
	v_and_b32_e32 v95, 0xffff0000, v54
	v_lshlrev_b32_e32 v97, 16, v55
	v_and_b32_e32 v99, 0xffff0000, v55
	v_lshlrev_b32_e32 v101, 16, v56
	v_and_b32_e32 v103, 0xffff0000, v56
	v_lshlrev_b32_e32 v105, 16, v57
	v_and_b32_e32 v107, 0xffff0000, v57
	v_lshlrev_b32_e32 v109, 16, v58
	v_and_b32_e32 v111, 0xffff0000, v58
	v_lshlrev_b32_e32 v113, 16, v59
	v_and_b32_e32 v115, 0xffff0000, v59
	v_pk_add_f32 v[32:33], v[84:85], v[86:87]
	v_pk_add_f32 v[34:35], v[92:93], v[94:95]
	v_pk_add_f32 v[36:37], v[100:101], v[102:103]
	v_pk_add_f32 v[38:39], v[108:109], v[110:111]
	v_pk_add_f32 v[32:33], v[32:33], v[88:89]
	v_pk_add_f32 v[34:35], v[34:35], v[96:97]
	v_pk_add_f32 v[36:37], v[36:37], v[104:105]
	v_pk_add_f32 v[38:39], v[38:39], v[112:113]
	v_pk_add_f32 v[32:33], v[32:33], v[90:91]
	v_pk_add_f32 v[34:35], v[34:35], v[98:99]
	v_pk_add_f32 v[36:37], v[36:37], v[106:107]
	v_pk_add_f32 v[38:39], v[38:39], v[114:115]
	v_pk_add_f32 v[148:149], v[32:33], v[34:35]
	v_pk_add_f32 v[148:149], v[148:149], v[36:37]
	v_pk_add_f32 v[148:149], v[148:149], v[38:39]
	ds_bpermute_b32 v150, v77, v148
	ds_bpermute_b32 v151, v77, v149
	s_waitcnt lgkmcnt(0)
	v_pk_add_f32 v[148:149], v[148:149], v[150:151]
	ds_bpermute_b32 v150, v78, v148
	ds_bpermute_b32 v151, v78, v149
	s_waitcnt lgkmcnt(0)
	v_pk_add_f32 v[148:149], v[148:149], v[150:151]
	ds_bpermute_b32 v150, v79, v148
	ds_bpermute_b32 v151, v79, v149
	s_waitcnt lgkmcnt(0)
	v_pk_add_f32 v[148:149], v[148:149], v[150:151]
	ds_bpermute_b32 v150, v80, v148
	ds_bpermute_b32 v151, v80, v149
	s_waitcnt lgkmcnt(0)
	v_pk_add_f32 v[148:149], v[148:149], v[150:151]
	ds_bpermute_b32 v150, v81, v148
	ds_bpermute_b32 v151, v81, v149
	s_waitcnt lgkmcnt(0)
	v_pk_add_f32 v[148:149], v[148:149], v[150:151]
	ds_bpermute_b32 v150, v82, v148
	ds_bpermute_b32 v151, v82, v149
	s_waitcnt lgkmcnt(0)
	v_pk_add_f32 v[148:149], v[148:149], v[150:151]
	v_mul_f32_e32 v148, 0x3a800000, v148
	v_mul_f32_e32 v149, 0x3a800000, v149
	v_pk_add_f32 v[84:85], v[84:85], v[148:149] neg_lo:[0,1] neg_hi:[0,1]
	v_pk_add_f32 v[86:87], v[86:87], v[148:149] neg_lo:[0,1] neg_hi:[0,1]
	v_pk_add_f32 v[88:89], v[88:89], v[148:149] neg_lo:[0,1] neg_hi:[0,1]
	v_pk_add_f32 v[90:91], v[90:91], v[148:149] neg_lo:[0,1] neg_hi:[0,1]
	v_pk_add_f32 v[92:93], v[92:93], v[148:149] neg_lo:[0,1] neg_hi:[0,1]
	v_pk_add_f32 v[94:95], v[94:95], v[148:149] neg_lo:[0,1] neg_hi:[0,1]
	v_pk_add_f32 v[96:97], v[96:97], v[148:149] neg_lo:[0,1] neg_hi:[0,1]
	v_pk_add_f32 v[98:99], v[98:99], v[148:149] neg_lo:[0,1] neg_hi:[0,1]
	v_pk_add_f32 v[100:101], v[100:101], v[148:149] neg_lo:[0,1] neg_hi:[0,1]
	v_pk_add_f32 v[102:103], v[102:103], v[148:149] neg_lo:[0,1] neg_hi:[0,1]
	v_pk_add_f32 v[104:105], v[104:105], v[148:149] neg_lo:[0,1] neg_hi:[0,1]
	v_pk_add_f32 v[106:107], v[106:107], v[148:149] neg_lo:[0,1] neg_hi:[0,1]
	v_pk_add_f32 v[108:109], v[108:109], v[148:149] neg_lo:[0,1] neg_hi:[0,1]
	v_pk_add_f32 v[110:111], v[110:111], v[148:149] neg_lo:[0,1] neg_hi:[0,1]
	v_pk_add_f32 v[112:113], v[112:113], v[148:149] neg_lo:[0,1] neg_hi:[0,1]
	v_pk_add_f32 v[114:115], v[114:115], v[148:149] neg_lo:[0,1] neg_hi:[0,1]
	v_pk_mul_f32 v[32:33], v[86:87], v[86:87]
	v_pk_mul_f32 v[34:35], v[94:95], v[94:95]
	v_pk_mul_f32 v[36:37], v[102:103], v[102:103]
	v_pk_mul_f32 v[38:39], v[110:111], v[110:111]
	v_pk_fma_f32 v[32:33], v[84:85], v[84:85], v[32:33]
	v_pk_fma_f32 v[34:35], v[92:93], v[92:93], v[34:35]
	v_pk_fma_f32 v[36:37], v[100:101], v[100:101], v[36:37]
	v_pk_fma_f32 v[38:39], v[108:109], v[108:109], v[38:39]
	v_pk_fma_f32 v[32:33], v[88:89], v[88:89], v[32:33]
	v_pk_fma_f32 v[34:35], v[96:97], v[96:97], v[34:35]
	v_pk_fma_f32 v[36:37], v[104:105], v[104:105], v[36:37]
	v_pk_fma_f32 v[38:39], v[112:113], v[112:113], v[38:39]
	v_pk_fma_f32 v[32:33], v[90:91], v[90:91], v[32:33]
	v_pk_fma_f32 v[34:35], v[98:99], v[98:99], v[34:35]
	v_pk_fma_f32 v[36:37], v[106:107], v[106:107], v[36:37]
	v_pk_fma_f32 v[38:39], v[114:115], v[114:115], v[38:39]
	v_pk_add_f32 v[150:151], v[32:33], v[34:35]
	v_pk_add_f32 v[150:151], v[36:37], v[150:151]
	v_pk_add_f32 v[150:151], v[38:39], v[150:151]
	ds_bpermute_b32 v36, v77, v150
	ds_bpermute_b32 v37, v77, v151
	s_waitcnt lgkmcnt(0)
	v_pk_add_f32 v[150:151], v[150:151], v[36:37]
	ds_bpermute_b32 v36, v78, v150
	ds_bpermute_b32 v37, v78, v151
	s_waitcnt lgkmcnt(0)
	v_pk_add_f32 v[150:151], v[150:151], v[36:37]
	ds_bpermute_b32 v36, v79, v150
	ds_bpermute_b32 v37, v79, v151
	s_waitcnt lgkmcnt(0)
	v_pk_add_f32 v[150:151], v[150:151], v[36:37]
	ds_bpermute_b32 v36, v80, v150
	ds_bpermute_b32 v37, v80, v151
	s_waitcnt lgkmcnt(0)
	v_pk_add_f32 v[150:151], v[150:151], v[36:37]
	ds_bpermute_b32 v36, v81, v150
	ds_bpermute_b32 v37, v81, v151
	s_waitcnt lgkmcnt(0)
	v_pk_add_f32 v[150:151], v[150:151], v[36:37]
	ds_bpermute_b32 v36, v82, v150
	ds_bpermute_b32 v37, v82, v151
	s_waitcnt lgkmcnt(0)
	v_pk_add_f32 v[150:151], v[150:151], v[36:37]
	v_fmamk_f32 v150, v150, 0x3a800000, v154
	v_fmamk_f32 v151, v151, 0x3a800000, v154
	v_rsq_f32_e32 v150, v150
	v_rsq_f32_e32 v151, v151
	s_nop 1
	v_mov_b32_e32 v32, v148
	v_mov_b32_e32 v33, v150
	v_mov_b32_e32 v34, v149
	v_mov_b32_e32 v35, v151
	s_mov_b64 exec, 1
	global_store_dwordx4 v153, v[32:35], s[68:69]
	s_mov_b64 exec, s[40:41]
	v_pk_mul_f32 v[84:85], v[84:85], v[150:151]
	v_pk_mul_f32 v[86:87], v[86:87], v[150:151]
	v_pk_mul_f32 v[88:89], v[88:89], v[150:151]
	v_pk_mul_f32 v[90:91], v[90:91], v[150:151]
	v_pk_mul_f32 v[92:93], v[92:93], v[150:151]
	v_pk_mul_f32 v[94:95], v[94:95], v[150:151]
	v_pk_mul_f32 v[96:97], v[96:97], v[150:151]
	v_pk_mul_f32 v[98:99], v[98:99], v[150:151]
	v_pk_mul_f32 v[100:101], v[100:101], v[150:151]
	v_pk_mul_f32 v[102:103], v[102:103], v[150:151]
	v_pk_mul_f32 v[104:105], v[104:105], v[150:151]
	v_pk_mul_f32 v[106:107], v[106:107], v[150:151]
	v_pk_mul_f32 v[108:109], v[108:109], v[150:151]
	v_pk_mul_f32 v[110:111], v[110:111], v[150:151]
	v_pk_mul_f32 v[112:113], v[112:113], v[150:151]
	v_pk_mul_f32 v[114:115], v[114:115], v[150:151]
	v_pk_fma_f32 v[84:85], v[0:1], v[84:85], v[8:9] op_sel:[0,0,0] op_sel_hi:[0,1,0]
	v_pk_fma_f32 v[86:87], v[0:1], v[86:87], v[8:9] op_sel:[1,0,1] op_sel_hi:[1,1,1]
	v_pk_fma_f32 v[88:89], v[2:3], v[88:89], v[10:11] op_sel:[0,0,0] op_sel_hi:[0,1,0]
	v_pk_fma_f32 v[90:91], v[2:3], v[90:91], v[10:11] op_sel:[1,0,1] op_sel_hi:[1,1,1]
	v_pk_fma_f32 v[92:93], v[4:5], v[92:93], v[12:13] op_sel:[0,0,0] op_sel_hi:[0,1,0]
	v_pk_fma_f32 v[94:95], v[4:5], v[94:95], v[12:13] op_sel:[1,0,1] op_sel_hi:[1,1,1]
	v_pk_fma_f32 v[96:97], v[6:7], v[96:97], v[14:15] op_sel:[0,0,0] op_sel_hi:[0,1,0]
	v_pk_fma_f32 v[98:99], v[6:7], v[98:99], v[14:15] op_sel:[1,0,1] op_sel_hi:[1,1,1]
	v_pk_fma_f32 v[100:101], v[16:17], v[100:101], v[24:25] op_sel:[0,0,0] op_sel_hi:[0,1,0]
	v_pk_fma_f32 v[102:103], v[16:17], v[102:103], v[24:25] op_sel:[1,0,1] op_sel_hi:[1,1,1]
	v_pk_fma_f32 v[104:105], v[18:19], v[104:105], v[26:27] op_sel:[0,0,0] op_sel_hi:[0,1,0]
	v_pk_fma_f32 v[106:107], v[18:19], v[106:107], v[26:27] op_sel:[1,0,1] op_sel_hi:[1,1,1]
	v_pk_fma_f32 v[108:109], v[20:21], v[108:109], v[28:29] op_sel:[0,0,0] op_sel_hi:[0,1,0]
	v_pk_fma_f32 v[110:111], v[20:21], v[110:111], v[28:29] op_sel:[1,0,1] op_sel_hi:[1,1,1]
	v_pk_fma_f32 v[112:113], v[22:23], v[112:113], v[30:31] op_sel:[0,0,0] op_sel_hi:[0,1,0]
	v_pk_fma_f32 v[114:115], v[22:23], v[114:115], v[30:31] op_sel:[1,0,1] op_sel_hi:[1,1,1]
	v_pk_fma_f32 v[84:85], v[84:85], v[132:133], v[116:117] op_sel:[0,0,0] op_sel_hi:[1,0,0]
	v_pk_fma_f32 v[86:87], v[86:87], v[132:133], v[116:117] op_sel:[0,1,1] op_sel_hi:[1,1,1]
	v_pk_fma_f32 v[88:89], v[88:89], v[134:135], v[118:119] op_sel:[0,0,0] op_sel_hi:[1,0,0]
	v_pk_fma_f32 v[90:91], v[90:91], v[134:135], v[118:119] op_sel:[0,1,1] op_sel_hi:[1,1,1]
	v_pk_fma_f32 v[92:93], v[92:93], v[136:137], v[120:121] op_sel:[0,0,0] op_sel_hi:[1,0,0]
	v_pk_fma_f32 v[94:95], v[94:95], v[136:137], v[120:121] op_sel:[0,1,1] op_sel_hi:[1,1,1]
	v_pk_fma_f32 v[96:97], v[96:97], v[138:139], v[122:123] op_sel:[0,0,0] op_sel_hi:[1,0,0]
	v_pk_fma_f32 v[98:99], v[98:99], v[138:139], v[122:123] op_sel:[0,1,1] op_sel_hi:[1,1,1]
	v_pk_fma_f32 v[100:101], v[100:101], v[140:141], v[124:125] op_sel:[0,0,0] op_sel_hi:[1,0,0]
	v_pk_fma_f32 v[102:103], v[102:103], v[140:141], v[124:125] op_sel:[0,1,1] op_sel_hi:[1,1,1]
	v_pk_fma_f32 v[104:105], v[104:105], v[142:143], v[126:127] op_sel:[0,0,0] op_sel_hi:[1,0,0]
	v_pk_fma_f32 v[106:107], v[106:107], v[142:143], v[126:127] op_sel:[0,1,1] op_sel_hi:[1,1,1]
	v_pk_fma_f32 v[108:109], v[108:109], v[144:145], v[128:129] op_sel:[0,0,0] op_sel_hi:[1,0,0]
	v_pk_fma_f32 v[110:111], v[110:111], v[144:145], v[128:129] op_sel:[0,1,1] op_sel_hi:[1,1,1]
	v_pk_fma_f32 v[112:113], v[112:113], v[146:147], v[130:131] op_sel:[0,0,0] op_sel_hi:[1,0,0]
	v_pk_fma_f32 v[114:115], v[114:115], v[146:147], v[130:131] op_sel:[0,1,1] op_sel_hi:[1,1,1]
	v_cvt_pk_bf16_f32 v44, v84, v86
	v_cvt_pk_bf16_f32 v45, v88, v90
	v_cvt_pk_bf16_f32 v46, v92, v94
	v_cvt_pk_bf16_f32 v47, v96, v98
	v_cvt_pk_bf16_f32 v48, v100, v102
	v_cvt_pk_bf16_f32 v49, v104, v106
	v_cvt_pk_bf16_f32 v50, v108, v110
	v_cvt_pk_bf16_f32 v51, v112, v114
	v_cvt_pk_bf16_f32 v52, v85, v87
	v_cvt_pk_bf16_f32 v53, v89, v91
	v_cvt_pk_bf16_f32 v54, v93, v95
	v_cvt_pk_bf16_f32 v55, v97, v99
	v_cvt_pk_bf16_f32 v56, v101, v103
	v_cvt_pk_bf16_f32 v57, v105, v107
	v_cvt_pk_bf16_f32 v58, v109, v111
	v_cvt_pk_bf16_f32 v59, v113, v115
	global_store_dwordx2 v41, v[44:45], s[54:55]
	global_store_dwordx2 v41, v[46:47], s[54:55] offset:512
	global_store_dwordx2 v41, v[48:49], s[54:55] offset:1024
	global_store_dwordx2 v41, v[50:51], s[54:55] offset:1536
	global_store_dwordx2 v41, v[52:53], s[54:55] offset:2048
	global_store_dwordx2 v41, v[54:55], s[54:55] offset:2560
	global_store_dwordx2 v41, v[56:57], s[54:55] offset:3072
	global_store_dwordx2 v41, v[58:59], s[54:55] offset:3584
	s_cmp_ge_i32 s73, s74
	s_cbranch_scc1 .Llna_exit
	s_mov_b32 s72, s73
.Llna_loop:
	s_lshl_b32 s1, s72, 11
	s_add_u32 s54, s58, s1
	s_addc_u32 s55, s59, 0
	s_add_u32 s54, s54, 0x9a10000
	s_addc_u32 s55, s55, 0
	s_lshl_b32 s1, s72, 3
	s_add_u32 s68, s58, s1
	s_addc_u32 s69, s59, 0
	s_add_u32 s68, s68, 0x910000
	s_addc_u32 s69, s69, 0
	s_lshr_b32 s1, s72, 12
	s_cmp_eq_u32 s1, s75
	s_cbranch_scc1 .Llna_mk1
	s_mov_b32 s75, s1
	s_add_i32 s1, s1, s0
	s_mul_i32 s1, s1, 0x6000
	s_add_u32 s70, s58, s1
	s_addc_u32 s71, s59, 0
	global_load_dwordx4 v[116:119], v42, s[70:71]
	global_load_dwordx4 v[120:123], v42, s[70:71] offset:1024
	global_load_dwordx4 v[124:127], v42, s[70:71] offset:2048
	global_load_dwordx4 v[128:131], v42, s[70:71] offset:3072
	global_load_dwordx4 v[132:135], v43, s[70:71]
	global_load_dwordx4 v[136:139], v43, s[70:71] offset:1024
	global_load_dwordx4 v[140:143], v43, s[70:71] offset:2048
	global_load_dwordx4 v[144:147], v43, s[70:71] offset:3072
	s_waitcnt vmcnt(0)
	v_pk_add_f32 v[132:133], v[132:133], 1.0 op_sel_hi:[1,0]
	v_pk_add_f32 v[134:135], v[134:135], 1.0 op_sel_hi:[1,0]
	v_pk_add_f32 v[136:137], v[136:137], 1.0 op_sel_hi:[1,0]
	v_pk_add_f32 v[138:139], v[138:139], 1.0 op_sel_hi:[1,0]
	v_pk_add_f32 v[140:141], v[140:141], 1.0 op_sel_hi:[1,0]
	v_pk_add_f32 v[142:143], v[142:143], 1.0 op_sel_hi:[1,0]
	v_pk_add_f32 v[144:145], v[144:145], 1.0 op_sel_hi:[1,0]
	v_pk_add_f32 v[146:147], v[146:147], 1.0 op_sel_hi:[1,0]
.Llna_mk1:
	s_add_i32 s73, s72, 2
	s_cmp_ge_i32 s73, s74
	s_cbranch_scc1 .Llna_np1
	s_lshl_b32 s1, s73, 11
	s_add_u32 s28, s58, s1
	s_addc_u32 s29, s59, 0
	s_add_u32 s28, s28, 0xa10000
	s_addc_u32 s29, s29, 0
	global_load_dwordx2 v[44:45], v41, s[28:29] nt
	global_load_dwordx2 v[46:47], v41, s[28:29] offset:512 nt
	global_load_dwordx2 v[48:49], v41, s[28:29] offset:1024 nt
	global_load_dwordx2 v[50:51], v41, s[28:29] offset:1536 nt
	global_load_dwordx2 v[52:53], v41, s[28:29] offset:2048 nt
	global_load_dwordx2 v[54:55], v41, s[28:29] offset:2560 nt
	global_load_dwordx2 v[56:57], v41, s[28:29] offset:3072 nt
	global_load_dwordx2 v[58:59], v41, s[28:29] offset:3584 nt
	s_waitcnt vmcnt(17)
	s_branch .Llna_go1
.Llna_np1:
	s_waitcnt vmcnt(9)
.Llna_go1:
	v_lshlrev_b32_e32 v84, 16, v60
	v_and_b32_e32 v86, 0xffff0000, v60
	v_lshlrev_b32_e32 v88, 16, v61
	v_and_b32_e32 v90, 0xffff0000, v61
	v_lshlrev_b32_e32 v92, 16, v62
	v_and_b32_e32 v94, 0xffff0000, v62
	v_lshlrev_b32_e32 v96, 16, v63
	v_and_b32_e32 v98, 0xffff0000, v63
	v_lshlrev_b32_e32 v100, 16, v64
	v_and_b32_e32 v102, 0xffff0000, v64
	v_lshlrev_b32_e32 v104, 16, v65
	v_and_b32_e32 v106, 0xffff0000, v65
	v_lshlrev_b32_e32 v108, 16, v66
	v_and_b32_e32 v110, 0xffff0000, v66
	v_lshlrev_b32_e32 v112, 16, v67
	v_and_b32_e32 v114, 0xffff0000, v67
	v_lshlrev_b32_e32 v85, 16, v68
	v_and_b32_e32 v87, 0xffff0000, v68
	v_lshlrev_b32_e32 v89, 16, v69
	v_and_b32_e32 v91, 0xffff0000, v69
	v_lshlrev_b32_e32 v93, 16, v70
	v_and_b32_e32 v95, 0xffff0000, v70
	v_lshlrev_b32_e32 v97, 16, v71
	v_and_b32_e32 v99, 0xffff0000, v71
	v_lshlrev_b32_e32 v101, 16, v72
	v_and_b32_e32 v103, 0xffff0000, v72
	v_lshlrev_b32_e32 v105, 16, v73
	v_and_b32_e32 v107, 0xffff0000, v73
	v_lshlrev_b32_e32 v109, 16, v74
	v_and_b32_e32 v111, 0xffff0000, v74
	v_lshlrev_b32_e32 v113, 16, v75
	v_and_b32_e32 v115, 0xffff0000, v75
	v_pk_add_f32 v[32:33], v[84:85], v[86:87]
	v_pk_add_f32 v[34:35], v[92:93], v[94:95]
	v_pk_add_f32 v[36:37], v[100:101], v[102:103]
	v_pk_add_f32 v[38:39], v[108:109], v[110:111]
	v_pk_add_f32 v[32:33], v[32:33], v[88:89]
	v_pk_add_f32 v[34:35], v[34:35], v[96:97]
	v_pk_add_f32 v[36:37], v[36:37], v[104:105]
	v_pk_add_f32 v[38:39], v[38:39], v[112:113]
	v_pk_add_f32 v[32:33], v[32:33], v[90:91]
	v_pk_add_f32 v[34:35], v[34:35], v[98:99]
	v_pk_add_f32 v[36:37], v[36:37], v[106:107]
	v_pk_add_f32 v[38:39], v[38:39], v[114:115]
	v_pk_add_f32 v[148:149], v[32:33], v[34:35]
	v_pk_add_f32 v[148:149], v[148:149], v[36:37]
	v_pk_add_f32 v[148:149], v[148:149], v[38:39]
	ds_bpermute_b32 v150, v77, v148
	ds_bpermute_b32 v151, v77, v149
	s_waitcnt lgkmcnt(0)
	v_pk_add_f32 v[148:149], v[148:149], v[150:151]
	ds_bpermute_b32 v150, v78, v148
	ds_bpermute_b32 v151, v78, v149
	s_waitcnt lgkmcnt(0)
	v_pk_add_f32 v[148:149], v[148:149], v[150:151]
	ds_bpermute_b32 v150, v79, v148
	ds_bpermute_b32 v151, v79, v149
	s_waitcnt lgkmcnt(0)
	v_pk_add_f32 v[148:149], v[148:149], v[150:151]
	ds_bpermute_b32 v150, v80, v148
	ds_bpermute_b32 v151, v80, v149
	s_waitcnt lgkmcnt(0)
	v_pk_add_f32 v[148:149], v[148:149], v[150:151]
	ds_bpermute_b32 v150, v81, v148
	ds_bpermute_b32 v151, v81, v149
	s_waitcnt lgkmcnt(0)
	v_pk_add_f32 v[148:149], v[148:149], v[150:151]
	ds_bpermute_b32 v150, v82, v148
	ds_bpermute_b32 v151, v82, v149
	s_waitcnt lgkmcnt(0)
	v_pk_add_f32 v[148:149], v[148:149], v[150:151]
	v_mul_f32_e32 v148, 0x3a800000, v148
	v_mul_f32_e32 v149, 0x3a800000, v149
	v_pk_add_f32 v[84:85], v[84:85], v[148:149] neg_lo:[0,1] neg_hi:[0,1]
	v_pk_add_f32 v[86:87], v[86:87], v[148:149] neg_lo:[0,1] neg_hi:[0,1]
	v_pk_add_f32 v[88:89], v[88:89], v[148:149] neg_lo:[0,1] neg_hi:[0,1]
	v_pk_add_f32 v[90:91], v[90:91], v[148:149] neg_lo:[0,1] neg_hi:[0,1]
	v_pk_add_f32 v[92:93], v[92:93], v[148:149] neg_lo:[0,1] neg_hi:[0,1]
	v_pk_add_f32 v[94:95], v[94:95], v[148:149] neg_lo:[0,1] neg_hi:[0,1]
	v_pk_add_f32 v[96:97], v[96:97], v[148:149] neg_lo:[0,1] neg_hi:[0,1]
	v_pk_add_f32 v[98:99], v[98:99], v[148:149] neg_lo:[0,1] neg_hi:[0,1]
	v_pk_add_f32 v[100:101], v[100:101], v[148:149] neg_lo:[0,1] neg_hi:[0,1]
	v_pk_add_f32 v[102:103], v[102:103], v[148:149] neg_lo:[0,1] neg_hi:[0,1]
	v_pk_add_f32 v[104:105], v[104:105], v[148:149] neg_lo:[0,1] neg_hi:[0,1]
	v_pk_add_f32 v[106:107], v[106:107], v[148:149] neg_lo:[0,1] neg_hi:[0,1]
	v_pk_add_f32 v[108:109], v[108:109], v[148:149] neg_lo:[0,1] neg_hi:[0,1]
	v_pk_add_f32 v[110:111], v[110:111], v[148:149] neg_lo:[0,1] neg_hi:[0,1]
	v_pk_add_f32 v[112:113], v[112:113], v[148:149] neg_lo:[0,1] neg_hi:[0,1]
	v_pk_add_f32 v[114:115], v[114:115], v[148:149] neg_lo:[0,1] neg_hi:[0,1]
	v_pk_mul_f32 v[32:33], v[86:87], v[86:87]
	v_pk_mul_f32 v[34:35], v[94:95], v[94:95]
	v_pk_mul_f32 v[36:37], v[102:103], v[102:103]
	v_pk_mul_f32 v[38:39], v[110:111], v[110:111]
	v_pk_fma_f32 v[32:33], v[84:85], v[84:85], v[32:33]
	v_pk_fma_f32 v[34:35], v[92:93], v[92:93], v[34:35]
	v_pk_fma_f32 v[36:37], v[100:101], v[100:101], v[36:37]
	v_pk_fma_f32 v[38:39], v[108:109], v[108:109], v[38:39]
	v_pk_fma_f32 v[32:33], v[88:89], v[88:89], v[32:33]
	v_pk_fma_f32 v[34:35], v[96:97], v[96:97], v[34:35]
	v_pk_fma_f32 v[36:37], v[104:105], v[104:105], v[36:37]
	v_pk_fma_f32 v[38:39], v[112:113], v[112:113], v[38:39]
	v_pk_fma_f32 v[32:33], v[90:91], v[90:91], v[32:33]
	v_pk_fma_f32 v[34:35], v[98:99], v[98:99], v[34:35]
	v_pk_fma_f32 v[36:37], v[106:107], v[106:107], v[36:37]
	v_pk_fma_f32 v[38:39], v[114:115], v[114:115], v[38:39]
	v_pk_add_f32 v[150:151], v[32:33], v[34:35]
	v_pk_add_f32 v[150:151], v[36:37], v[150:151]
	v_pk_add_f32 v[150:151], v[38:39], v[150:151]
	ds_bpermute_b32 v36, v77, v150
	ds_bpermute_b32 v37, v77, v151
	s_waitcnt lgkmcnt(0)
	v_pk_add_f32 v[150:151], v[150:151], v[36:37]
	ds_bpermute_b32 v36, v78, v150
	ds_bpermute_b32 v37, v78, v151
	s_waitcnt lgkmcnt(0)
	v_pk_add_f32 v[150:151], v[150:151], v[36:37]
	ds_bpermute_b32 v36, v79, v150
	ds_bpermute_b32 v37, v79, v151
	s_waitcnt lgkmcnt(0)
	v_pk_add_f32 v[150:151], v[150:151], v[36:37]
	ds_bpermute_b32 v36, v80, v150
	ds_bpermute_b32 v37, v80, v151
	s_waitcnt lgkmcnt(0)
	v_pk_add_f32 v[150:151], v[150:151], v[36:37]
	ds_bpermute_b32 v36, v81, v150
	ds_bpermute_b32 v37, v81, v151
	s_waitcnt lgkmcnt(0)
	v_pk_add_f32 v[150:151], v[150:151], v[36:37]
	ds_bpermute_b32 v36, v82, v150
	ds_bpermute_b32 v37, v82, v151
	s_waitcnt lgkmcnt(0)
	v_pk_add_f32 v[150:151], v[150:151], v[36:37]
	v_fmamk_f32 v150, v150, 0x3a800000, v154
	v_fmamk_f32 v151, v151, 0x3a800000, v154
	v_rsq_f32_e32 v150, v150
	v_rsq_f32_e32 v151, v151
	s_nop 1
	v_mov_b32_e32 v32, v148
	v_mov_b32_e32 v33, v150
	v_mov_b32_e32 v34, v149
	v_mov_b32_e32 v35, v151
	s_mov_b64 exec, 1
	global_store_dwordx4 v153, v[32:35], s[68:69]
	s_mov_b64 exec, s[40:41]
	v_pk_mul_f32 v[84:85], v[84:85], v[150:151]
	v_pk_mul_f32 v[86:87], v[86:87], v[150:151]
	v_pk_mul_f32 v[88:89], v[88:89], v[150:151]
	v_pk_mul_f32 v[90:91], v[90:91], v[150:151]
	v_pk_mul_f32 v[92:93], v[92:93], v[150:151]
	v_pk_mul_f32 v[94:95], v[94:95], v[150:151]
	v_pk_mul_f32 v[96:97], v[96:97], v[150:151]
	v_pk_mul_f32 v[98:99], v[98:99], v[150:151]
	v_pk_mul_f32 v[100:101], v[100:101], v[150:151]
	v_pk_mul_f32 v[102:103], v[102:103], v[150:151]
	v_pk_mul_f32 v[104:105], v[104:105], v[150:151]
	v_pk_mul_f32 v[106:107], v[106:107], v[150:151]
	v_pk_mul_f32 v[108:109], v[108:109], v[150:151]
	v_pk_mul_f32 v[110:111], v[110:111], v[150:151]
	v_pk_mul_f32 v[112:113], v[112:113], v[150:151]
	v_pk_mul_f32 v[114:115], v[114:115], v[150:151]
	v_pk_fma_f32 v[84:85], v[0:1], v[84:85], v[8:9] op_sel:[0,0,0] op_sel_hi:[0,1,0]
	v_pk_fma_f32 v[86:87], v[0:1], v[86:87], v[8:9] op_sel:[1,0,1] op_sel_hi:[1,1,1]
	v_pk_fma_f32 v[88:89], v[2:3], v[88:89], v[10:11] op_sel:[0,0,0] op_sel_hi:[0,1,0]
	v_pk_fma_f32 v[90:91], v[2:3], v[90:91], v[10:11] op_sel:[1,0,1] op_sel_hi:[1,1,1]
	v_pk_fma_f32 v[92:93], v[4:5], v[92:93], v[12:13] op_sel:[0,0,0] op_sel_hi:[0,1,0]
	v_pk_fma_f32 v[94:95], v[4:5], v[94:95], v[12:13] op_sel:[1,0,1] op_sel_hi:[1,1,1]
	v_pk_fma_f32 v[96:97], v[6:7], v[96:97], v[14:15] op_sel:[0,0,0] op_sel_hi:[0,1,0]
	v_pk_fma_f32 v[98:99], v[6:7], v[98:99], v[14:15] op_sel:[1,0,1] op_sel_hi:[1,1,1]
	v_pk_fma_f32 v[100:101], v[16:17], v[100:101], v[24:25] op_sel:[0,0,0] op_sel_hi:[0,1,0]
	v_pk_fma_f32 v[102:103], v[16:17], v[102:103], v[24:25] op_sel:[1,0,1] op_sel_hi:[1,1,1]
	v_pk_fma_f32 v[104:105], v[18:19], v[104:105], v[26:27] op_sel:[0,0,0] op_sel_hi:[0,1,0]
	v_pk_fma_f32 v[106:107], v[18:19], v[106:107], v[26:27] op_sel:[1,0,1] op_sel_hi:[1,1,1]
	v_pk_fma_f32 v[108:109], v[20:21], v[108:109], v[28:29] op_sel:[0,0,0] op_sel_hi:[0,1,0]
	v_pk_fma_f32 v[110:111], v[20:21], v[110:111], v[28:29] op_sel:[1,0,1] op_sel_hi:[1,1,1]
	v_pk_fma_f32 v[112:113], v[22:23], v[112:113], v[30:31] op_sel:[0,0,0] op_sel_hi:[0,1,0]
	v_pk_fma_f32 v[114:115], v[22:23], v[114:115], v[30:31] op_sel:[1,0,1] op_sel_hi:[1,1,1]
	v_pk_fma_f32 v[84:85], v[84:85], v[132:133], v[116:117] op_sel:[0,0,0] op_sel_hi:[1,0,0]
	v_pk_fma_f32 v[86:87], v[86:87], v[132:133], v[116:117] op_sel:[0,1,1] op_sel_hi:[1,1,1]
	v_pk_fma_f32 v[88:89], v[88:89], v[134:135], v[118:119] op_sel:[0,0,0] op_sel_hi:[1,0,0]
	v_pk_fma_f32 v[90:91], v[90:91], v[134:135], v[118:119] op_sel:[0,1,1] op_sel_hi:[1,1,1]
	v_pk_fma_f32 v[92:93], v[92:93], v[136:137], v[120:121] op_sel:[0,0,0] op_sel_hi:[1,0,0]
	v_pk_fma_f32 v[94:95], v[94:95], v[136:137], v[120:121] op_sel:[0,1,1] op_sel_hi:[1,1,1]
	v_pk_fma_f32 v[96:97], v[96:97], v[138:139], v[122:123] op_sel:[0,0,0] op_sel_hi:[1,0,0]
	v_pk_fma_f32 v[98:99], v[98:99], v[138:139], v[122:123] op_sel:[0,1,1] op_sel_hi:[1,1,1]
	v_pk_fma_f32 v[100:101], v[100:101], v[140:141], v[124:125] op_sel:[0,0,0] op_sel_hi:[1,0,0]
	v_pk_fma_f32 v[102:103], v[102:103], v[140:141], v[124:125] op_sel:[0,1,1] op_sel_hi:[1,1,1]
	v_pk_fma_f32 v[104:105], v[104:105], v[142:143], v[126:127] op_sel:[0,0,0] op_sel_hi:[1,0,0]
	v_pk_fma_f32 v[106:107], v[106:107], v[142:143], v[126:127] op_sel:[0,1,1] op_sel_hi:[1,1,1]
	v_pk_fma_f32 v[108:109], v[108:109], v[144:145], v[128:129] op_sel:[0,0,0] op_sel_hi:[1,0,0]
	v_pk_fma_f32 v[110:111], v[110:111], v[144:145], v[128:129] op_sel:[0,1,1] op_sel_hi:[1,1,1]
	v_pk_fma_f32 v[112:113], v[112:113], v[146:147], v[130:131] op_sel:[0,0,0] op_sel_hi:[1,0,0]
	v_pk_fma_f32 v[114:115], v[114:115], v[146:147], v[130:131] op_sel:[0,1,1] op_sel_hi:[1,1,1]
	v_cvt_pk_bf16_f32 v60, v84, v86
	v_cvt_pk_bf16_f32 v61, v88, v90
	v_cvt_pk_bf16_f32 v62, v92, v94
	v_cvt_pk_bf16_f32 v63, v96, v98
	v_cvt_pk_bf16_f32 v64, v100, v102
	v_cvt_pk_bf16_f32 v65, v104, v106
	v_cvt_pk_bf16_f32 v66, v108, v110
	v_cvt_pk_bf16_f32 v67, v112, v114
	v_cvt_pk_bf16_f32 v68, v85, v87
	v_cvt_pk_bf16_f32 v69, v89, v91
	v_cvt_pk_bf16_f32 v70, v93, v95
	v_cvt_pk_bf16_f32 v71, v97, v99
	v_cvt_pk_bf16_f32 v72, v101, v103
	v_cvt_pk_bf16_f32 v73, v105, v107
	v_cvt_pk_bf16_f32 v74, v109, v111
	v_cvt_pk_bf16_f32 v75, v113, v115
	global_store_dwordx2 v41, v[60:61], s[54:55]
	global_store_dwordx2 v41, v[62:63], s[54:55] offset:512
	global_store_dwordx2 v41, v[64:65], s[54:55] offset:1024
	global_store_dwordx2 v41, v[66:67], s[54:55] offset:1536
	global_store_dwordx2 v41, v[68:69], s[54:55] offset:2048
	global_store_dwordx2 v41, v[70:71], s[54:55] offset:2560
	global_store_dwordx2 v41, v[72:73], s[54:55] offset:3072
	global_store_dwordx2 v41, v[74:75], s[54:55] offset:3584
	s_cmp_ge_i32 s73, s74
	s_cbranch_scc1 .Llna_exit
	s_mov_b32 s72, s73
	s_lshl_b32 s1, s72, 11
	s_add_u32 s54, s58, s1
	s_addc_u32 s55, s59, 0
	s_add_u32 s54, s54, 0x9a10000
	s_addc_u32 s55, s55, 0
	s_lshl_b32 s1, s72, 3
	s_add_u32 s68, s58, s1
	s_addc_u32 s69, s59, 0
	s_add_u32 s68, s68, 0x910000
	s_addc_u32 s69, s69, 0
	s_lshr_b32 s1, s72, 12
	s_cmp_eq_u32 s1, s75
	s_cbranch_scc1 .Llna_mk2
	s_mov_b32 s75, s1
	s_add_i32 s1, s1, s0
	s_mul_i32 s1, s1, 0x6000
	s_add_u32 s70, s58, s1
	s_addc_u32 s71, s59, 0
	global_load_dwordx4 v[116:119], v42, s[70:71]
	global_load_dwordx4 v[120:123], v42, s[70:71] offset:1024
	global_load_dwordx4 v[124:127], v42, s[70:71] offset:2048
	global_load_dwordx4 v[128:131], v42, s[70:71] offset:3072
	global_load_dwordx4 v[132:135], v43, s[70:71]
	global_load_dwordx4 v[136:139], v43, s[70:71] offset:1024
	global_load_dwordx4 v[140:143], v43, s[70:71] offset:2048
	global_load_dwordx4 v[144:147], v43, s[70:71] offset:3072
	s_waitcnt vmcnt(0)
	v_pk_add_f32 v[132:133], v[132:133], 1.0 op_sel_hi:[1,0]
	v_pk_add_f32 v[134:135], v[134:135], 1.0 op_sel_hi:[1,0]
	v_pk_add_f32 v[136:137], v[136:137], 1.0 op_sel_hi:[1,0]
	v_pk_add_f32 v[138:139], v[138:139], 1.0 op_sel_hi:[1,0]
	v_pk_add_f32 v[140:141], v[140:141], 1.0 op_sel_hi:[1,0]
	v_pk_add_f32 v[142:143], v[142:143], 1.0 op_sel_hi:[1,0]
	v_pk_add_f32 v[144:145], v[144:145], 1.0 op_sel_hi:[1,0]
	v_pk_add_f32 v[146:147], v[146:147], 1.0 op_sel_hi:[1,0]
.Llna_mk2:
	s_add_i32 s73, s72, 2
	s_cmp_ge_i32 s73, s74
	s_cbranch_scc1 .Llna_np2
	s_lshl_b32 s1, s73, 11
	s_add_u32 s28, s58, s1
	s_addc_u32 s29, s59, 0
	s_add_u32 s28, s28, 0xa10000
	s_addc_u32 s29, s29, 0
	global_load_dwordx2 v[60:61], v41, s[28:29] nt
	global_load_dwordx2 v[62:63], v41, s[28:29] offset:512 nt
	global_load_dwordx2 v[64:65], v41, s[28:29] offset:1024 nt
	global_load_dwordx2 v[66:67], v41, s[28:29] offset:1536 nt
	global_load_dwordx2 v[68:69], v41, s[28:29] offset:2048 nt
	global_load_dwordx2 v[70:71], v41, s[28:29] offset:2560 nt
	global_load_dwordx2 v[72:73], v41, s[28:29] offset:3072 nt
	global_load_dwordx2 v[74:75], v41, s[28:29] offset:3584 nt
	s_waitcnt vmcnt(17)
	s_branch .Llna_go2

.Llna_go2:
	v_lshlrev_b32_e32 v84, 16, v44
	v_and_b32_e32 v86, 0xffff0000, v44
	v_lshlrev_b32_e32 v88, 16, v45
	v_and_b32_e32 v90, 0xffff0000, v45
	v_lshlrev_b32_e32 v92, 16, v46
	v_and_b32_e32 v94, 0xffff0000, v46
	v_lshlrev_b32_e32 v96, 16, v47
	v_and_b32_e32 v98, 0xffff0000, v47
	v_lshlrev_b32_e32 v100, 16, v48
	v_and_b32_e32 v102, 0xffff0000, v48
	v_lshlrev_b32_e32 v104, 16, v49
	v_and_b32_e32 v106, 0xffff0000, v49
	v_lshlrev_b32_e32 v108, 16, v50
	v_and_b32_e32 v110, 0xffff0000, v50
	v_lshlrev_b32_e32 v112, 16, v51
	v_and_b32_e32 v114, 0xffff0000, v51
	v_lshlrev_b32_e32 v85, 16, v52
	v_and_b32_e32 v87, 0xffff0000, v52
	v_lshlrev_b32_e32 v89, 16, v53
	v_and_b32_e32 v91, 0xffff0000, v53
	v_lshlrev_b32_e32 v93, 16, v54
	v_and_b32_e32 v95, 0xffff0000, v54
	v_lshlrev_b32_e32 v97, 16, v55
	v_and_b32_e32 v99, 0xffff0000, v55
	v_lshlrev_b32_e32 v101, 16, v56
	v_and_b32_e32 v103, 0xffff0000, v56
	v_lshlrev_b32_e32 v105, 16, v57
	v_and_b32_e32 v107, 0xffff0000, v57
	v_lshlrev_b32_e32 v109, 16, v58
	v_and_b32_e32 v111, 0xffff0000, v58
	v_lshlrev_b32_e32 v113, 16, v59
	v_and_b32_e32 v115, 0xffff0000, v59
	v_pk_add_f32 v[32:33], v[84:85], v[86:87]
	v_pk_add_f32 v[34:35], v[92:93], v[94:95]
	v_pk_add_f32 v[36:37], v[100:101], v[102:103]
	v_pk_add_f32 v[38:39], v[108:109], v[110:111]
	v_pk_add_f32 v[32:33], v[32:33], v[88:89]
	v_pk_add_f32 v[34:35], v[34:35], v[96:97]
	v_pk_add_f32 v[36:37], v[36:37], v[104:105]
	v_pk_add_f32 v[38:39], v[38:39], v[112:113]
	v_pk_add_f32 v[32:33], v[32:33], v[90:91]
	v_pk_add_f32 v[34:35], v[34:35], v[98:99]
	v_pk_add_f32 v[36:37], v[36:37], v[106:107]
	v_pk_add_f32 v[38:39], v[38:39], v[114:115]
	v_pk_add_f32 v[148:149], v[32:33], v[34:35]
	v_pk_add_f32 v[148:149], v[148:149], v[36:37]
	v_pk_add_f32 v[148:149], v[148:149], v[38:39]
	ds_bpermute_b32 v150, v77, v148
	ds_bpermute_b32 v151, v77, v149
	s_waitcnt lgkmcnt(0)
	v_pk_add_f32 v[148:149], v[148:149], v[150:151]
	ds_bpermute_b32 v150, v78, v148
	ds_bpermute_b32 v151, v78, v149
	s_waitcnt lgkmcnt(0)
	v_pk_add_f32 v[148:149], v[148:149], v[150:151]
	ds_bpermute_b32 v150, v79, v148
	ds_bpermute_b32 v151, v79, v149
	s_waitcnt lgkmcnt(0)
	v_pk_add_f32 v[148:149], v[148:149], v[150:151]
	ds_bpermute_b32 v150, v80, v148
	ds_bpermute_b32 v151, v80, v149
	s_waitcnt lgkmcnt(0)
	v_pk_add_f32 v[148:149], v[148:149], v[150:151]
	ds_bpermute_b32 v150, v81, v148
	ds_bpermute_b32 v151, v81, v149
	s_waitcnt lgkmcnt(0)
	v_pk_add_f32 v[148:149], v[148:149], v[150:151]
	ds_bpermute_b32 v150, v82, v148
	ds_bpermute_b32 v151, v82, v149
	s_waitcnt lgkmcnt(0)
	v_pk_add_f32 v[148:149], v[148:149], v[150:151]
	v_mul_f32_e32 v148, 0x3a800000, v148
	v_mul_f32_e32 v149, 0x3a800000, v149
	v_pk_add_f32 v[84:85], v[84:85], v[148:149] neg_lo:[0,1] neg_hi:[0,1]
	v_pk_add_f32 v[86:87], v[86:87], v[148:149] neg_lo:[0,1] neg_hi:[0,1]
	v_pk_add_f32 v[88:89], v[88:89], v[148:149] neg_lo:[0,1] neg_hi:[0,1]
	v_pk_add_f32 v[90:91], v[90:91], v[148:149] neg_lo:[0,1] neg_hi:[0,1]
	v_pk_add_f32 v[92:93], v[92:93], v[148:149] neg_lo:[0,1] neg_hi:[0,1]
	v_pk_add_f32 v[94:95], v[94:95], v[148:149] neg_lo:[0,1] neg_hi:[0,1]
	v_pk_add_f32 v[96:97], v[96:97], v[148:149] neg_lo:[0,1] neg_hi:[0,1]
	v_pk_add_f32 v[98:99], v[98:99], v[148:149] neg_lo:[0,1] neg_hi:[0,1]
	v_pk_add_f32 v[100:101], v[100:101], v[148:149] neg_lo:[0,1] neg_hi:[0,1]
	v_pk_add_f32 v[102:103], v[102:103], v[148:149] neg_lo:[0,1] neg_hi:[0,1]
	v_pk_add_f32 v[104:105], v[104:105], v[148:149] neg_lo:[0,1] neg_hi:[0,1]
	v_pk_add_f32 v[106:107], v[106:107], v[148:149] neg_lo:[0,1] neg_hi:[0,1]
	v_pk_add_f32 v[108:109], v[108:109], v[148:149] neg_lo:[0,1] neg_hi:[0,1]
	v_pk_add_f32 v[110:111], v[110:111], v[148:149] neg_lo:[0,1] neg_hi:[0,1]
	v_pk_add_f32 v[112:113], v[112:113], v[148:149] neg_lo:[0,1] neg_hi:[0,1]
	v_pk_add_f32 v[114:115], v[114:115], v[148:149] neg_lo:[0,1] neg_hi:[0,1]
	v_pk_mul_f32 v[32:33], v[86:87], v[86:87]
	v_pk_mul_f32 v[34:35], v[94:95], v[94:95]
	v_pk_mul_f32 v[36:37], v[102:103], v[102:103]
	v_pk_mul_f32 v[38:39], v[110:111], v[110:111]
	v_pk_fma_f32 v[32:33], v[84:85], v[84:85], v[32:33]
	v_pk_fma_f32 v[34:35], v[92:93], v[92:93], v[34:35]
	v_pk_fma_f32 v[36:37], v[100:101], v[100:101], v[36:37]
	v_pk_fma_f32 v[38:39], v[108:109], v[108:109], v[38:39]
	v_pk_fma_f32 v[32:33], v[88:89], v[88:89], v[32:33]
	v_pk_fma_f32 v[34:35], v[96:97], v[96:97], v[34:35]
	v_pk_fma_f32 v[36:37], v[104:105], v[104:105], v[36:37]
	v_pk_fma_f32 v[38:39], v[112:113], v[112:113], v[38:39]
	v_pk_fma_f32 v[32:33], v[90:91], v[90:91], v[32:33]
	v_pk_fma_f32 v[34:35], v[98:99], v[98:99], v[34:35]
	v_pk_fma_f32 v[36:37], v[106:107], v[106:107], v[36:37]
	v_pk_fma_f32 v[38:39], v[114:115], v[114:115], v[38:39]
	v_pk_add_f32 v[150:151], v[32:33], v[34:35]
	v_pk_add_f32 v[150:151], v[36:37], v[150:151]
	v_pk_add_f32 v[150:151], v[38:39], v[150:151]
	ds_bpermute_b32 v36, v77, v150
	ds_bpermute_b32 v37, v77, v151
	s_waitcnt lgkmcnt(0)
	v_pk_add_f32 v[150:151], v[150:151], v[36:37]
	ds_bpermute_b32 v36, v78, v150
	ds_bpermute_b32 v37, v78, v151
	s_waitcnt lgkmcnt(0)
	v_pk_add_f32 v[150:151], v[150:151], v[36:37]
	ds_bpermute_b32 v36, v79, v150
	ds_bpermute_b32 v37, v79, v151
	s_waitcnt lgkmcnt(0)
	v_pk_add_f32 v[150:151], v[150:151], v[36:37]
	ds_bpermute_b32 v36, v80, v150
	ds_bpermute_b32 v37, v80, v151
	s_waitcnt lgkmcnt(0)
	v_pk_add_f32 v[150:151], v[150:151], v[36:37]
	ds_bpermute_b32 v36, v81, v150
	ds_bpermute_b32 v37, v81, v151
	s_waitcnt lgkmcnt(0)
	v_pk_add_f32 v[150:151], v[150:151], v[36:37]
	ds_bpermute_b32 v36, v82, v150
	ds_bpermute_b32 v37, v82, v151
	s_waitcnt lgkmcnt(0)
	v_pk_add_f32 v[150:151], v[150:151], v[36:37]
	v_fmamk_f32 v150, v150, 0x3a800000, v154
	v_fmamk_f32 v151, v151, 0x3a800000, v154
	v_rsq_f32_e32 v150, v150
	v_rsq_f32_e32 v151, v151
	s_nop 1
	v_mov_b32_e32 v32, v148
	v_mov_b32_e32 v33, v150
	v_mov_b32_e32 v34, v149
	v_mov_b32_e32 v35, v151
	s_mov_b64 exec, 1
	global_store_dwordx4 v153, v[32:35], s[68:69]
	s_mov_b64 exec, s[40:41]
	v_pk_mul_f32 v[84:85], v[84:85], v[150:151]
	v_pk_mul_f32 v[86:87], v[86:87], v[150:151]
	v_pk_mul_f32 v[88:89], v[88:89], v[150:151]
	v_pk_mul_f32 v[90:91], v[90:91], v[150:151]
	v_pk_mul_f32 v[92:93], v[92:93], v[150:151]
	v_pk_mul_f32 v[94:95], v[94:95], v[150:151]
	v_pk_mul_f32 v[96:97], v[96:97], v[150:151]
	v_pk_mul_f32 v[98:99], v[98:99], v[150:151]
	v_pk_mul_f32 v[100:101], v[100:101], v[150:151]
	v_pk_mul_f32 v[102:103], v[102:103], v[150:151]
	v_pk_mul_f32 v[104:105], v[104:105], v[150:151]
	v_pk_mul_f32 v[106:107], v[106:107], v[150:151]
	v_pk_mul_f32 v[108:109], v[108:109], v[150:151]
	v_pk_mul_f32 v[110:111], v[110:111], v[150:151]
	v_pk_mul_f32 v[112:113], v[112:113], v[150:151]
	v_pk_mul_f32 v[114:115], v[114:115], v[150:151]
	v_pk_fma_f32 v[84:85], v[0:1], v[84:85], v[8:9] op_sel:[0,0,0] op_sel_hi:[0,1,0]
	v_pk_fma_f32 v[86:87], v[0:1], v[86:87], v[8:9] op_sel:[1,0,1] op_sel_hi:[1,1,1]
	v_pk_fma_f32 v[88:89], v[2:3], v[88:89], v[10:11] op_sel:[0,0,0] op_sel_hi:[0,1,0]
	v_pk_fma_f32 v[90:91], v[2:3], v[90:91], v[10:11] op_sel:[1,0,1] op_sel_hi:[1,1,1]
	v_pk_fma_f32 v[92:93], v[4:5], v[92:93], v[12:13] op_sel:[0,0,0] op_sel_hi:[0,1,0]
	v_pk_fma_f32 v[94:95], v[4:5], v[94:95], v[12:13] op_sel:[1,0,1] op_sel_hi:[1,1,1]
	v_pk_fma_f32 v[96:97], v[6:7], v[96:97], v[14:15] op_sel:[0,0,0] op_sel_hi:[0,1,0]
	v_pk_fma_f32 v[98:99], v[6:7], v[98:99], v[14:15] op_sel:[1,0,1] op_sel_hi:[1,1,1]
	v_pk_fma_f32 v[100:101], v[16:17], v[100:101], v[24:25] op_sel:[0,0,0] op_sel_hi:[0,1,0]
	v_pk_fma_f32 v[102:103], v[16:17], v[102:103], v[24:25] op_sel:[1,0,1] op_sel_hi:[1,1,1]
	v_pk_fma_f32 v[104:105], v[18:19], v[104:105], v[26:27] op_sel:[0,0,0] op_sel_hi:[0,1,0]
	v_pk_fma_f32 v[106:107], v[18:19], v[106:107], v[26:27] op_sel:[1,0,1] op_sel_hi:[1,1,1]
	v_pk_fma_f32 v[108:109], v[20:21], v[108:109], v[28:29] op_sel:[0,0,0] op_sel_hi:[0,1,0]
	v_pk_fma_f32 v[110:111], v[20:21], v[110:111], v[28:29] op_sel:[1,0,1] op_sel_hi:[1,1,1]
	v_pk_fma_f32 v[112:113], v[22:23], v[112:113], v[30:31] op_sel:[0,0,0] op_sel_hi:[0,1,0]
	v_pk_fma_f32 v[114:115], v[22:23], v[114:115], v[30:31] op_sel:[1,0,1] op_sel_hi:[1,1,1]
	v_pk_fma_f32 v[84:85], v[84:85], v[132:133], v[116:117] op_sel:[0,0,0] op_sel_hi:[1,0,0]
	v_pk_fma_f32 v[86:87], v[86:87], v[132:133], v[116:117] op_sel:[0,1,1] op_sel_hi:[1,1,1]
	v_pk_fma_f32 v[88:89], v[88:89], v[134:135], v[118:119] op_sel:[0,0,0] op_sel_hi:[1,0,0]
	v_pk_fma_f32 v[90:91], v[90:91], v[134:135], v[118:119] op_sel:[0,1,1] op_sel_hi:[1,1,1]
	v_pk_fma_f32 v[92:93], v[92:93], v[136:137], v[120:121] op_sel:[0,0,0] op_sel_hi:[1,0,0]
	v_pk_fma_f32 v[94:95], v[94:95], v[136:137], v[120:121] op_sel:[0,1,1] op_sel_hi:[1,1,1]
	v_pk_fma_f32 v[96:97], v[96:97], v[138:139], v[122:123] op_sel:[0,0,0] op_sel_hi:[1,0,0]
	v_pk_fma_f32 v[98:99], v[98:99], v[138:139], v[122:123] op_sel:[0,1,1] op_sel_hi:[1,1,1]
	v_pk_fma_f32 v[100:101], v[100:101], v[140:141], v[124:125] op_sel:[0,0,0] op_sel_hi:[1,0,0]
	v_pk_fma_f32 v[102:103], v[102:103], v[140:141], v[124:125] op_sel:[0,1,1] op_sel_hi:[1,1,1]
	v_pk_fma_f32 v[104:105], v[104:105], v[142:143], v[126:127] op_sel:[0,0,0] op_sel_hi:[1,0,0]
	v_pk_fma_f32 v[106:107], v[106:107], v[142:143], v[126:127] op_sel:[0,1,1] op_sel_hi:[1,1,1]
	v_pk_fma_f32 v[108:109], v[108:109], v[144:145], v[128:129] op_sel:[0,0,0] op_sel_hi:[1,0,0]
	v_pk_fma_f32 v[110:111], v[110:111], v[144:145], v[128:129] op_sel:[0,1,1] op_sel_hi:[1,1,1]
	v_pk_fma_f32 v[112:113], v[112:113], v[146:147], v[130:131] op_sel:[0,0,0] op_sel_hi:[1,0,0]
	v_pk_fma_f32 v[114:115], v[114:115], v[146:147], v[130:131] op_sel:[0,1,1] op_sel_hi:[1,1,1]
	v_cvt_pk_bf16_f32 v44, v84, v86
	v_cvt_pk_bf16_f32 v45, v88, v90
	v_cvt_pk_bf16_f32 v46, v92, v94
	v_cvt_pk_bf16_f32 v47, v96, v98
	v_cvt_pk_bf16_f32 v48, v100, v102
	v_cvt_pk_bf16_f32 v49, v104, v106
	v_cvt_pk_bf16_f32 v50, v108, v110
	v_cvt_pk_bf16_f32 v51, v112, v114
	v_cvt_pk_bf16_f32 v52, v85, v87
	v_cvt_pk_bf16_f32 v53, v89, v91
	v_cvt_pk_bf16_f32 v54, v93, v95
	v_cvt_pk_bf16_f32 v55, v97, v99
	v_cvt_pk_bf16_f32 v56, v101, v103
	v_cvt_pk_bf16_f32 v57, v105, v107
	v_cvt_pk_bf16_f32 v58, v109, v111
	v_cvt_pk_bf16_f32 v59, v113, v115
	global_store_dwordx2 v41, v[44:45], s[54:55]
	global_store_dwordx2 v41, v[46:47], s[54:55] offset:512
	global_store_dwordx2 v41, v[48:49], s[54:55] offset:1024
	global_store_dwordx2 v41, v[50:51], s[54:55] offset:1536
	global_store_dwordx2 v41, v[52:53], s[54:55] offset:2048
	global_store_dwordx2 v41, v[54:55], s[54:55] offset:2560
	global_store_dwordx2 v41, v[56:57], s[54:55] offset:3072
	global_store_dwordx2 v41, v[58:59], s[54:55] offset:3584
	s_cmp_ge_i32 s73, s74
	s_cbranch_scc1 .Llna_exit
	s_mov_b32 s72, s73
	s_branch .Llna_loop

.LBB0_271:
	s_andn2_b64 vcc, exec, s[42:43]
	s_cbranch_vccnz .LBB0_280
	v_readfirstlane_b32 s0, v155
	v_mbcnt_lo_u32_b32 v0, -1, 0
	v_mbcnt_hi_u32_b32 v0, -1, v0
	s_waitcnt vmcnt(0) lgkmcnt(0)
	s_nop 0
	v_or_b32_e32 v1, s0, v0
	v_ashrrev_i32_e32 v1, 5, v1
	v_and_b32_e32 v1, -2, v1
	v_readlane_b32 s0, v252, 58
	s_nop 1
	v_add_u32_e32 v32, s0, v1
	s_mov_b32 s0, 0x9000
	v_cmp_gt_i32_e32 vcc, s0, v32
	s_and_saveexec_b64 s[42:43], vcc
	s_cbranch_execz .LBB0_279
	v_readlane_b32 s7, v255, 17
	s_lshl_b32 s2, s7, 13
	v_readlane_b32 s0, v255, 9
	v_readlane_b32 s1, v255, 10
	s_add_u32 s0, s0, s2
	v_and_b32_e32 v40, 63, v0
	s_addc_u32 s1, s1, 0
	v_readlane_b32 s16, v255, 11
	v_readlane_b32 s17, v255, 12
	s_add_u32 s28, s16, s2
	v_lshlrev_b32_e32 v34, 4, v40
	s_addc_u32 s29, s17, 0
	s_waitcnt lgkmcnt(0)
	global_load_dwordx4 v[0:3], v34, s[0:1]
	global_load_dwordx4 v[4:7], v34, s[0:1] offset:1024
	global_load_dwordx4 v[8:11], v34, s[28:29]
	global_load_dwordx4 v[12:15], v34, s[28:29] offset:1024
	global_load_dwordx4 v[16:19], v34, s[0:1] offset:2048
	global_load_dwordx4 v[20:23], v34, s[0:1] offset:3072
	global_load_dwordx4 v[24:27], v34, s[28:29] offset:2048
	global_load_dwordx4 v[28:31], v34, s[28:29] offset:3072
	v_readlane_b32 s0, v252, 59
	v_readlane_b32 s1, v252, 60
	s_load_dword s1, s[0:1], 0x0
	v_lshlrev_b32_e32 v33, 2, v40
	v_xor_b32_e32 v77, 0x80, v33
	v_xor_b32_e32 v78, 64, v33
	v_xor_b32_e32 v79, 32, v33
	v_xor_b32_e32 v80, 16, v33
	v_xor_b32_e32 v81, 8, v33
	v_xor_b32_e32 v82, 4, v33
	v_ashrrev_i32_e32 v33, 31, v32
	s_waitcnt lgkmcnt(0)
	s_lshl_b32 s44, s1, 4
	v_readlane_b32 s68, v254, 44
	v_lshlrev_b64 v[38:39], 11, v[32:33]
	v_mov_b32_e32 v35, v153
	v_readlane_b32 s72, v254, 48
	v_readlane_b32 s73, v254, 49
	s_ashr_i32 s45, s44, 31
	v_lshl_or_b32 v38, v40, 3, v38
	v_cmp_eq_u32_e64 s[40:41], 0, v40
	s_mul_i32 s0, s7, 9
	v_lshl_add_u64 v[34:35], s[58:59], 0, v[34:35]
	v_lshl_add_u64 v[36:37], v[32:33], 3, s[72:73]
	s_lshl_b64 s[50:51], s[44:45], 3
	v_lshl_add_u64 v[38:39], s[72:73], 0, v[38:39]
	s_lshl_b64 s[52:53], s[44:45], 11
	s_mov_b64 s[54:55], 0
	v_readlane_b32 s69, v254, 45
	v_readlane_b32 s70, v254, 46
	v_readlane_b32 s71, v254, 47
	v_readlane_b32 s74, v254, 50
	v_readlane_b32 s75, v254, 51
	s_mov_b64 s[40:41], exec
	v_readfirstlane_b32 s72, v32
	v_lshlrev_b32_e32 v41, 3, v40
	v_lshlrev_b32_e32 v42, 4, v40
	v_add_u32_e32 v43, 0x1000, v42
	s_nop 3
	s_lshr_b32 s16, s44, 1
	s_mov_b32 s17, 0
	s_mov_b32 s1, 0
.Llnb_div:
	s_add_i32 s17, s17, s16
	s_add_i32 s1, s1, 1
	s_cmpk_lt_u32 s17, 0x4800
	s_cbranch_scc1 .Llnb_div
	s_lshl_b32 s1, s1, 1
	s_lshr_b32 s72, s72, 1
	s_mul_i32 s72, s72, s1
	s_add_i32 s74, s72, s1
	s_min_i32 s74, s74, 0x9000
	s_mov_b32 s75, -1
	s_cmp_ge_i32 s72, s74
	s_cbranch_scc1 .Llnb_exit
	s_lshl_b32 s1, s72, 11
	s_add_u32 s28, s58, s1
	s_addc_u32 s29, s59, 0
	s_add_u32 s28, s28, 0xa10000
	s_addc_u32 s29, s29, 0
	global_load_dwordx2 v[44:45], v41, s[28:29] nt
	global_load_dwordx2 v[46:47], v41, s[28:29] offset:512 nt
	global_load_dwordx2 v[48:49], v41, s[28:29] offset:1024 nt
	global_load_dwordx2 v[50:51], v41, s[28:29] offset:1536 nt
	global_load_dwordx2 v[52:53], v41, s[28:29] offset:2048 nt
	global_load_dwordx2 v[54:55], v41, s[28:29] offset:2560 nt
	global_load_dwordx2 v[56:57], v41, s[28:29] offset:3072 nt
	global_load_dwordx2 v[58:59], v41, s[28:29] offset:3584 nt
	s_lshl_b32 s1, s72, 11
	s_add_u32 s54, s58, s1
	s_addc_u32 s55, s59, 0
	s_add_u32 s54, s54, 0x9a10000
	s_addc_u32 s55, s55, 0
	s_lshl_b32 s1, s72, 3
	s_add_u32 s68, s58, s1
	s_addc_u32 s69, s59, 0
	s_add_u32 s68, s68, 0x910000
	s_addc_u32 s69, s69, 0
	s_lshr_b32 s1, s72, 12
	s_cmp_eq_u32 s1, s75
	s_cbranch_scc1 .Llnb_mk0
	s_mov_b32 s75, s1
	s_add_i32 s1, s1, s0
	s_mul_i32 s1, s1, 0x6000
	s_add_i32 s1, s1, 0x3000
	s_add_u32 s70, s58, s1
	s_addc_u32 s71, s59, 0
	global_load_dwordx4 v[116:119], v42, s[70:71]
	global_load_dwordx4 v[120:123], v42, s[70:71] offset:1024
	global_load_dwordx4 v[124:127], v42, s[70:71] offset:2048
	global_load_dwordx4 v[128:131], v42, s[70:71] offset:3072
	global_load_dwordx4 v[132:135], v43, s[70:71]
	global_load_dwordx4 v[136:139], v43, s[70:71] offset:1024
	global_load_dwordx4 v[140:143], v43, s[70:71] offset:2048
	global_load_dwordx4 v[144:147], v43, s[70:71] offset:3072
	s_waitcnt vmcnt(0)
	v_pk_add_f32 v[132:133], v[132:133], 1.0 op_sel_hi:[1,0]
	v_pk_add_f32 v[134:135], v[134:135], 1.0 op_sel_hi:[1,0]
	v_pk_add_f32 v[136:137], v[136:137], 1.0 op_sel_hi:[1,0]
	v_pk_add_f32 v[138:139], v[138:139], 1.0 op_sel_hi:[1,0]
	v_pk_add_f32 v[140:141], v[140:141], 1.0 op_sel_hi:[1,0]
	v_pk_add_f32 v[142:143], v[142:143], 1.0 op_sel_hi:[1,0]
	v_pk_add_f32 v[144:145], v[144:145], 1.0 op_sel_hi:[1,0]
	v_pk_add_f32 v[146:147], v[146:147], 1.0 op_sel_hi:[1,0]

.Llnb_loop:
	s_lshl_b32 s1, s72, 11
	s_add_u32 s54, s58, s1
	s_addc_u32 s55, s59, 0
	s_add_u32 s54, s54, 0x9a10000
	s_addc_u32 s55, s55, 0
	s_lshl_b32 s1, s72, 3
	s_add_u32 s68, s58, s1
	s_addc_u32 s69, s59, 0
	s_add_u32 s68, s68, 0x910000
	s_addc_u32 s69, s69, 0
	s_lshr_b32 s1, s72, 12
	s_cmp_eq_u32 s1, s75
	s_cbranch_scc1 .Llnb_mk1
	s_mov_b32 s75, s1
	s_add_i32 s1, s1, s0
	s_mul_i32 s1, s1, 0x6000
	s_add_i32 s1, s1, 0x3000
	s_add_u32 s70, s58, s1
	s_addc_u32 s71, s59, 0
	global_load_dwordx4 v[116:119], v42, s[70:71]
	global_load_dwordx4 v[120:123], v42, s[70:71] offset:1024
	global_load_dwordx4 v[124:127], v42, s[70:71] offset:2048
	global_load_dwordx4 v[128:131], v42, s[70:71] offset:3072
	global_load_dwordx4 v[132:135], v43, s[70:71]
	global_load_dwordx4 v[136:139], v43, s[70:71] offset:1024
	global_load_dwordx4 v[140:143], v43, s[70:71] offset:2048
	global_load_dwordx4 v[144:147], v43, s[70:71] offset:3072
	s_waitcnt vmcnt(0)
	v_pk_add_f32 v[132:133], v[132:133], 1.0 op_sel_hi:[1,0]
	v_pk_add_f32 v[134:135], v[134:135], 1.0 op_sel_hi:[1,0]
	v_pk_add_f32 v[136:137], v[136:137], 1.0 op_sel_hi:[1,0]
	v_pk_add_f32 v[138:139], v[138:139], 1.0 op_sel_hi:[1,0]
	v_pk_add_f32 v[140:141], v[140:141], 1.0 op_sel_hi:[1,0]
	v_pk_add_f32 v[142:143], v[142:143], 1.0 op_sel_hi:[1,0]
	v_pk_add_f32 v[144:145], v[144:145], 1.0 op_sel_hi:[1,0]
	v_pk_add_f32 v[146:147], v[146:147], 1.0 op_sel_hi:[1,0]

.Llnb_go1:
	v_lshlrev_b32_e32 v84, 16, v60
	v_and_b32_e32 v86, 0xffff0000, v60
	v_lshlrev_b32_e32 v88, 16, v61
	v_and_b32_e32 v90, 0xffff0000, v61
	v_lshlrev_b32_e32 v92, 16, v62
	v_and_b32_e32 v94, 0xffff0000, v62
	v_lshlrev_b32_e32 v96, 16, v63
	v_and_b32_e32 v98, 0xffff0000, v63
	v_lshlrev_b32_e32 v100, 16, v64
	v_and_b32_e32 v102, 0xffff0000, v64
	v_lshlrev_b32_e32 v104, 16, v65
	v_and_b32_e32 v106, 0xffff0000, v65
	v_lshlrev_b32_e32 v108, 16, v66
	v_and_b32_e32 v110, 0xffff0000, v66
	v_lshlrev_b32_e32 v112, 16, v67
	v_and_b32_e32 v114, 0xffff0000, v67
	v_lshlrev_b32_e32 v85, 16, v68
	v_and_b32_e32 v87, 0xffff0000, v68
	v_lshlrev_b32_e32 v89, 16, v69
	v_and_b32_e32 v91, 0xffff0000, v69
	v_lshlrev_b32_e32 v93, 16, v70
	v_and_b32_e32 v95, 0xffff0000, v70
	v_lshlrev_b32_e32 v97, 16, v71
	v_and_b32_e32 v99, 0xffff0000, v71
	v_lshlrev_b32_e32 v101, 16, v72
	v_and_b32_e32 v103, 0xffff0000, v72
	v_lshlrev_b32_e32 v105, 16, v73
	v_and_b32_e32 v107, 0xffff0000, v73
	v_lshlrev_b32_e32 v109, 16, v74
	v_and_b32_e32 v111, 0xffff0000, v74
	v_lshlrev_b32_e32 v113, 16, v75
	v_and_b32_e32 v115, 0xffff0000, v75
	v_pk_add_f32 v[32:33], v[84:85], v[86:87]
	v_pk_add_f32 v[34:35], v[92:93], v[94:95]
	v_pk_add_f32 v[36:37], v[100:101], v[102:103]
	v_pk_add_f32 v[38:39], v[108:109], v[110:111]
	v_pk_add_f32 v[32:33], v[32:33], v[88:89]
	v_pk_add_f32 v[34:35], v[34:35], v[96:97]
	v_pk_add_f32 v[36:37], v[36:37], v[104:105]
	v_pk_add_f32 v[38:39], v[38:39], v[112:113]
	v_pk_add_f32 v[32:33], v[32:33], v[90:91]
	v_pk_add_f32 v[34:35], v[34:35], v[98:99]
	v_pk_add_f32 v[36:37], v[36:37], v[106:107]
	v_pk_add_f32 v[38:39], v[38:39], v[114:115]
	v_pk_add_f32 v[148:149], v[32:33], v[34:35]
	v_pk_add_f32 v[148:149], v[148:149], v[36:37]
	v_pk_add_f32 v[148:149], v[148:149], v[38:39]
	ds_bpermute_b32 v150, v77, v148
	ds_bpermute_b32 v151, v77, v149
	s_waitcnt lgkmcnt(0)
	v_pk_add_f32 v[148:149], v[148:149], v[150:151]
	ds_bpermute_b32 v150, v78, v148
	ds_bpermute_b32 v151, v78, v149
	s_waitcnt lgkmcnt(0)
	v_pk_add_f32 v[148:149], v[148:149], v[150:151]
	ds_bpermute_b32 v150, v79, v148
	ds_bpermute_b32 v151, v79, v149
	s_waitcnt lgkmcnt(0)
	v_pk_add_f32 v[148:149], v[148:149], v[150:151]
	ds_bpermute_b32 v150, v80, v148
	ds_bpermute_b32 v151, v80, v149
	s_waitcnt lgkmcnt(0)
	v_pk_add_f32 v[148:149], v[148:149], v[150:151]
	ds_bpermute_b32 v150, v81, v148
	ds_bpermute_b32 v151, v81, v149
	s_waitcnt lgkmcnt(0)
	v_pk_add_f32 v[148:149], v[148:149], v[150:151]
	ds_bpermute_b32 v150, v82, v148
	ds_bpermute_b32 v151, v82, v149
	s_waitcnt lgkmcnt(0)
	v_pk_add_f32 v[148:149], v[148:149], v[150:151]
	v_mul_f32_e32 v148, 0x3a800000, v148
	v_mul_f32_e32 v149, 0x3a800000, v149
	v_pk_add_f32 v[84:85], v[84:85], v[148:149] neg_lo:[0,1] neg_hi:[0,1]
	v_pk_add_f32 v[86:87], v[86:87], v[148:149] neg_lo:[0,1] neg_hi:[0,1]
	v_pk_add_f32 v[88:89], v[88:89], v[148:149] neg_lo:[0,1] neg_hi:[0,1]
	v_pk_add_f32 v[90:91], v[90:91], v[148:149] neg_lo:[0,1] neg_hi:[0,1]
	v_pk_add_f32 v[92:93], v[92:93], v[148:149] neg_lo:[0,1] neg_hi:[0,1]
	v_pk_add_f32 v[94:95], v[94:95], v[148:149] neg_lo:[0,1] neg_hi:[0,1]
	v_pk_add_f32 v[96:97], v[96:97], v[148:149] neg_lo:[0,1] neg_hi:[0,1]
	v_pk_add_f32 v[98:99], v[98:99], v[148:149] neg_lo:[0,1] neg_hi:[0,1]
	v_pk_add_f32 v[100:101], v[100:101], v[148:149] neg_lo:[0,1] neg_hi:[0,1]
	v_pk_add_f32 v[102:103], v[102:103], v[148:149] neg_lo:[0,1] neg_hi:[0,1]
	v_pk_add_f32 v[104:105], v[104:105], v[148:149] neg_lo:[0,1] neg_hi:[0,1]
	v_pk_add_f32 v[106:107], v[106:107], v[148:149] neg_lo:[0,1] neg_hi:[0,1]
	v_pk_add_f32 v[108:109], v[108:109], v[148:149] neg_lo:[0,1] neg_hi:[0,1]
	v_pk_add_f32 v[110:111], v[110:111], v[148:149] neg_lo:[0,1] neg_hi:[0,1]
	v_pk_add_f32 v[112:113], v[112:113], v[148:149] neg_lo:[0,1] neg_hi:[0,1]
	v_pk_add_f32 v[114:115], v[114:115], v[148:149] neg_lo:[0,1] neg_hi:[0,1]
	v_pk_mul_f32 v[32:33], v[86:87], v[86:87]
	v_pk_mul_f32 v[34:35], v[94:95], v[94:95]
	v_pk_mul_f32 v[36:37], v[102:103], v[102:103]
	v_pk_mul_f32 v[38:39], v[110:111], v[110:111]
	v_pk_fma_f32 v[32:33], v[84:85], v[84:85], v[32:33]
	v_pk_fma_f32 v[34:35], v[92:93], v[92:93], v[34:35]
	v_pk_fma_f32 v[36:37], v[100:101], v[100:101], v[36:37]
	v_pk_fma_f32 v[38:39], v[108:109], v[108:109], v[38:39]
	v_pk_fma_f32 v[32:33], v[88:89], v[88:89], v[32:33]
	v_pk_fma_f32 v[34:35], v[96:97], v[96:97], v[34:35]
	v_pk_fma_f32 v[36:37], v[104:105], v[104:105], v[36:37]
	v_pk_fma_f32 v[38:39], v[112:113], v[112:113], v[38:39]
	v_pk_fma_f32 v[32:33], v[90:91], v[90:91], v[32:33]
	v_pk_fma_f32 v[34:35], v[98:99], v[98:99], v[34:35]
	v_pk_fma_f32 v[36:37], v[106:107], v[106:107], v[36:37]
	v_pk_fma_f32 v[38:39], v[114:115], v[114:115], v[38:39]
	v_pk_add_f32 v[150:151], v[32:33], v[34:35]
	v_pk_add_f32 v[150:151], v[36:37], v[150:151]
	v_pk_add_f32 v[150:151], v[38:39], v[150:151]
	ds_bpermute_b32 v36, v77, v150
	ds_bpermute_b32 v37, v77, v151
	s_waitcnt lgkmcnt(0)
	v_pk_add_f32 v[150:151], v[150:151], v[36:37]
	ds_bpermute_b32 v36, v78, v150
	ds_bpermute_b32 v37, v78, v151
	s_waitcnt lgkmcnt(0)
	v_pk_add_f32 v[150:151], v[150:151], v[36:37]
	ds_bpermute_b32 v36, v79, v150
	ds_bpermute_b32 v37, v79, v151
	s_waitcnt lgkmcnt(0)
	v_pk_add_f32 v[150:151], v[150:151], v[36:37]
	ds_bpermute_b32 v36, v80, v150
	ds_bpermute_b32 v37, v80, v151
	s_waitcnt lgkmcnt(0)
	v_pk_add_f32 v[150:151], v[150:151], v[36:37]
	ds_bpermute_b32 v36, v81, v150
	ds_bpermute_b32 v37, v81, v151
	s_waitcnt lgkmcnt(0)
	v_pk_add_f32 v[150:151], v[150:151], v[36:37]
	ds_bpermute_b32 v36, v82, v150
	ds_bpermute_b32 v37, v82, v151
	s_waitcnt lgkmcnt(0)
	v_pk_add_f32 v[150:151], v[150:151], v[36:37]
	v_fmamk_f32 v150, v150, 0x3a800000, v154
	v_fmamk_f32 v151, v151, 0x3a800000, v154
	v_rsq_f32_e32 v150, v150
	v_rsq_f32_e32 v151, v151
	s_nop 1
	v_mov_b32_e32 v32, v148
	v_mov_b32_e32 v33, v150
	v_mov_b32_e32 v34, v149
	v_mov_b32_e32 v35, v151
	s_mov_b64 exec, 1
	global_store_dwordx4 v153, v[32:35], s[68:69]
	s_mov_b64 exec, s[40:41]
	v_pk_mul_f32 v[84:85], v[84:85], v[150:151]
	v_pk_mul_f32 v[86:87], v[86:87], v[150:151]
	v_pk_mul_f32 v[88:89], v[88:89], v[150:151]
	v_pk_mul_f32 v[90:91], v[90:91], v[150:151]
	v_pk_mul_f32 v[92:93], v[92:93], v[150:151]
	v_pk_mul_f32 v[94:95], v[94:95], v[150:151]
	v_pk_mul_f32 v[96:97], v[96:97], v[150:151]
	v_pk_mul_f32 v[98:99], v[98:99], v[150:151]
	v_pk_mul_f32 v[100:101], v[100:101], v[150:151]
	v_pk_mul_f32 v[102:103], v[102:103], v[150:151]
	v_pk_mul_f32 v[104:105], v[104:105], v[150:151]
	v_pk_mul_f32 v[106:107], v[106:107], v[150:151]
	v_pk_mul_f32 v[108:109], v[108:109], v[150:151]
	v_pk_mul_f32 v[110:111], v[110:111], v[150:151]
	v_pk_mul_f32 v[112:113], v[112:113], v[150:151]
	v_pk_mul_f32 v[114:115], v[114:115], v[150:151]
	v_pk_fma_f32 v[84:85], v[0:1], v[84:85], v[8:9] op_sel:[0,0,0] op_sel_hi:[0,1,0]
	v_pk_fma_f32 v[86:87], v[0:1], v[86:87], v[8:9] op_sel:[1,0,1] op_sel_hi:[1,1,1]
	v_pk_fma_f32 v[88:89], v[2:3], v[88:89], v[10:11] op_sel:[0,0,0] op_sel_hi:[0,1,0]
	v_pk_fma_f32 v[90:91], v[2:3], v[90:91], v[10:11] op_sel:[1,0,1] op_sel_hi:[1,1,1]
	v_pk_fma_f32 v[92:93], v[4:5], v[92:93], v[12:13] op_sel:[0,0,0] op_sel_hi:[0,1,0]
	v_pk_fma_f32 v[94:95], v[4:5], v[94:95], v[12:13] op_sel:[1,0,1] op_sel_hi:[1,1,1]
	v_pk_fma_f32 v[96:97], v[6:7], v[96:97], v[14:15] op_sel:[0,0,0] op_sel_hi:[0,1,0]
	v_pk_fma_f32 v[98:99], v[6:7], v[98:99], v[14:15] op_sel:[1,0,1] op_sel_hi:[1,1,1]
	v_pk_fma_f32 v[100:101], v[16:17], v[100:101], v[24:25] op_sel:[0,0,0] op_sel_hi:[0,1,0]
	v_pk_fma_f32 v[102:103], v[16:17], v[102:103], v[24:25] op_sel:[1,0,1] op_sel_hi:[1,1,1]
	v_pk_fma_f32 v[104:105], v[18:19], v[104:105], v[26:27] op_sel:[0,0,0] op_sel_hi:[0,1,0]
	v_pk_fma_f32 v[106:107], v[18:19], v[106:107], v[26:27] op_sel:[1,0,1] op_sel_hi:[1,1,1]
	v_pk_fma_f32 v[108:109], v[20:21], v[108:109], v[28:29] op_sel:[0,0,0] op_sel_hi:[0,1,0]
	v_pk_fma_f32 v[110:111], v[20:21], v[110:111], v[28:29] op_sel:[1,0,1] op_sel_hi:[1,1,1]
	v_pk_fma_f32 v[112:113], v[22:23], v[112:113], v[30:31] op_sel:[0,0,0] op_sel_hi:[0,1,0]
	v_pk_fma_f32 v[114:115], v[22:23], v[114:115], v[30:31] op_sel:[1,0,1] op_sel_hi:[1,1,1]
	v_pk_fma_f32 v[84:85], v[84:85], v[132:133], v[116:117] op_sel:[0,0,0] op_sel_hi:[1,0,0]
	v_pk_fma_f32 v[86:87], v[86:87], v[132:133], v[116:117] op_sel:[0,1,1] op_sel_hi:[1,1,1]
	v_pk_fma_f32 v[88:89], v[88:89], v[134:135], v[118:119] op_sel:[0,0,0] op_sel_hi:[1,0,0]
	v_pk_fma_f32 v[90:91], v[90:91], v[134:135], v[118:119] op_sel:[0,1,1] op_sel_hi:[1,1,1]
	v_pk_fma_f32 v[92:93], v[92:93], v[136:137], v[120:121] op_sel:[0,0,0] op_sel_hi:[1,0,0]
	v_pk_fma_f32 v[94:95], v[94:95], v[136:137], v[120:121] op_sel:[0,1,1] op_sel_hi:[1,1,1]
	v_pk_fma_f32 v[96:97], v[96:97], v[138:139], v[122:123] op_sel:[0,0,0] op_sel_hi:[1,0,0]
	v_pk_fma_f32 v[98:99], v[98:99], v[138:139], v[122:123] op_sel:[0,1,1] op_sel_hi:[1,1,1]
	v_pk_fma_f32 v[100:101], v[100:101], v[140:141], v[124:125] op_sel:[0,0,0] op_sel_hi:[1,0,0]
	v_pk_fma_f32 v[102:103], v[102:103], v[140:141], v[124:125] op_sel:[0,1,1] op_sel_hi:[1,1,1]
	v_pk_fma_f32 v[104:105], v[104:105], v[142:143], v[126:127] op_sel:[0,0,0] op_sel_hi:[1,0,0]
	v_pk_fma_f32 v[106:107], v[106:107], v[142:143], v[126:127] op_sel:[0,1,1] op_sel_hi:[1,1,1]
	v_pk_fma_f32 v[108:109], v[108:109], v[144:145], v[128:129] op_sel:[0,0,0] op_sel_hi:[1,0,0]
	v_pk_fma_f32 v[110:111], v[110:111], v[144:145], v[128:129] op_sel:[0,1,1] op_sel_hi:[1,1,1]
	v_pk_fma_f32 v[112:113], v[112:113], v[146:147], v[130:131] op_sel:[0,0,0] op_sel_hi:[1,0,0]
	v_pk_fma_f32 v[114:115], v[114:115], v[146:147], v[130:131] op_sel:[0,1,1] op_sel_hi:[1,1,1]
	v_cvt_pk_bf16_f32 v60, v84, v86
	v_cvt_pk_bf16_f32 v61, v88, v90
	v_cvt_pk_bf16_f32 v62, v92, v94
	v_cvt_pk_bf16_f32 v63, v96, v98
	v_cvt_pk_bf16_f32 v64, v100, v102
	v_cvt_pk_bf16_f32 v65, v104, v106
	v_cvt_pk_bf16_f32 v66, v108, v110
	v_cvt_pk_bf16_f32 v67, v112, v114
	v_cvt_pk_bf16_f32 v68, v85, v87
	v_cvt_pk_bf16_f32 v69, v89, v91
	v_cvt_pk_bf16_f32 v70, v93, v95
	v_cvt_pk_bf16_f32 v71, v97, v99
	v_cvt_pk_bf16_f32 v72, v101, v103
	v_cvt_pk_bf16_f32 v73, v105, v107
	v_cvt_pk_bf16_f32 v74, v109, v111
	v_cvt_pk_bf16_f32 v75, v113, v115
	global_store_dwordx2 v41, v[60:61], s[54:55]
	global_store_dwordx2 v41, v[62:63], s[54:55] offset:512
	global_store_dwordx2 v41, v[64:65], s[54:55] offset:1024
	global_store_dwordx2 v41, v[66:67], s[54:55] offset:1536
	global_store_dwordx2 v41, v[68:69], s[54:55] offset:2048
	global_store_dwordx2 v41, v[70:71], s[54:55] offset:2560
	global_store_dwordx2 v41, v[72:73], s[54:55] offset:3072
	global_store_dwordx2 v41, v[74:75], s[54:55] offset:3584
	s_cmp_ge_i32 s73, s74
	s_cbranch_scc1 .Llnb_exit
	s_mov_b32 s72, s73
	s_lshl_b32 s1, s72, 11
	s_add_u32 s54, s58, s1
	s_addc_u32 s55, s59, 0
	s_add_u32 s54, s54, 0x9a10000
	s_addc_u32 s55, s55, 0
	s_lshl_b32 s1, s72, 3
	s_add_u32 s68, s58, s1
	s_addc_u32 s69, s59, 0
	s_add_u32 s68, s68, 0x910000
	s_addc_u32 s69, s69, 0
	s_lshr_b32 s1, s72, 12
	s_cmp_eq_u32 s1, s75
	s_cbranch_scc1 .Llnb_mk2
	s_mov_b32 s75, s1
	s_add_i32 s1, s1, s0
	s_mul_i32 s1, s1, 0x6000
	s_add_i32 s1, s1, 0x3000
	s_add_u32 s70, s58, s1
	s_addc_u32 s71, s59, 0
	global_load_dwordx4 v[116:119], v42, s[70:71]
	global_load_dwordx4 v[120:123], v42, s[70:71] offset:1024
	global_load_dwordx4 v[124:127], v42, s[70:71] offset:2048
	global_load_dwordx4 v[128:131], v42, s[70:71] offset:3072
	global_load_dwordx4 v[132:135], v43, s[70:71]
	global_load_dwordx4 v[136:139], v43, s[70:71] offset:1024
	global_load_dwordx4 v[140:143], v43, s[70:71] offset:2048
	global_load_dwordx4 v[144:147], v43, s[70:71] offset:3072
	s_waitcnt vmcnt(0)
	v_pk_add_f32 v[132:133], v[132:133], 1.0 op_sel_hi:[1,0]
	v_pk_add_f32 v[134:135], v[134:135], 1.0 op_sel_hi:[1,0]
	v_pk_add_f32 v[136:137], v[136:137], 1.0 op_sel_hi:[1,0]
	v_pk_add_f32 v[138:139], v[138:139], 1.0 op_sel_hi:[1,0]
	v_pk_add_f32 v[140:141], v[140:141], 1.0 op_sel_hi:[1,0]
	v_pk_add_f32 v[142:143], v[142:143], 1.0 op_sel_hi:[1,0]
	v_pk_add_f32 v[144:145], v[144:145], 1.0 op_sel_hi:[1,0]
	v_pk_add_f32 v[146:147], v[146:147], 1.0 op_sel_hi:[1,0]

.LBB0_1351:
	s_waitcnt vmcnt(0)
	v_readlane_b32 s16, v254, 40
	v_readlane_b32 s17, v254, 41
	s_waitcnt vmcnt(0) lgkmcnt(0)
	s_barrier
	s_and_saveexec_b64 s[24:25], s[16:17]
	s_cbranch_execz .LBB0_1404
	v_readlane_b32 s1, v254, 38
	s_waitcnt vmcnt(0) expcnt(0) lgkmcnt(0)
	s_nop 0
	v_mov_b32_e32 v0, s1
	ds_read_b32 v2, v0
	v_readlane_b32 s1, v254, 39
	s_waitcnt lgkmcnt(0)
	v_cmp_ne_u32_e32 vcc, 0, v2
	v_mov_b32_e32 v0, s1
	ds_read_b32 v0, v0
	s_cbranch_vccnz .LBB0_1368
	v_readlane_b32 s16, v252, 59
	v_readlane_b32 s17, v252, 60
	s_load_dwordx2 s[26:27], s[16:17], 0x0
	s_load_dword s1, s[16:17], 0x8
	s_waitcnt lgkmcnt(0)
	s_mul_i32 s2, s27, s26
	s_mul_i32 s1, s2, s1
	s_mov_b32 s2, 1
	s_branch .LBB0_1356
